# wait counts made of loads only wherever loads and stores share the queue (selected-block epilogue, retention group-norm pass, residual epilogues: all stores after the last add): stores may retire out
# speedup vs baseline: 1.0830x; 1.0092x over previous
.Lintra_c_go:
	v_mov_b32_e32 v221, v208
	v_and_b32_e32 v221, 63, v221
	v_lshlrev_b32_e32 v221, 2, v221
	v_xor_b32_e32 v222, 64, v221
	v_xor_b32_e32 v221, 0x80, v221
	ds_bpermute_b32 v223, v222, v202
	ds_bpermute_b32 v224, v222, v203
	s_waitcnt lgkmcnt(0)
	v_add_f32_e32 v202, v202, v223
	v_add_f32_e32 v203, v203, v224
	ds_bpermute_b32 v223, v221, v202
	ds_bpermute_b32 v224, v221, v203
	s_waitcnt lgkmcnt(0)
	v_add_f32_e32 v202, v202, v223
	v_add_f32_e32 v203, v203, v224
	v_mul_f32_e32 v227, 0x3b000000, v202
	v_mul_f32_e32 v228, 0x3b000000, v203
	v_fma_f32 v228, -v227, v227, v228
	v_max_f32_e32 v228, 0, v228
	v_add_f32_e32 v228, 0x3727c5ac, v228
	v_rsq_f32_e32 v228, v228
	s_mul_i32 s0, s8, 0x1800
	s_add_u32 s30, s20, s0
	s_addc_u32 s31, s21, 0
	s_lshl_b32 s0, s8, 12
	s_add_u32 s34, s22, s0
	s_addc_u32 s35, s23, 0
	s_waitcnt vmcnt(0)
	global_load_dwordx2 v[24:25], v205, s[34:35] offset:0
	global_load_dwordx2 v[100:101], v204, s[30:31] offset:0
	global_load_dwordx4 v[68:71], v206, s[28:29] offset:0
	global_load_dwordx2 v[26:27], v205, s[34:35] offset:32
	global_load_dwordx2 v[102:103], v204, s[30:31] offset:32
	global_load_dwordx4 v[72:75], v206, s[28:29] offset:64
	global_load_dwordx2 v[28:29], v205, s[34:35] offset:64
	global_load_dwordx2 v[104:105], v204, s[30:31] offset:64
	global_load_dwordx4 v[76:79], v206, s[28:29] offset:128
	global_load_dwordx2 v[30:31], v205, s[34:35] offset:96
	global_load_dwordx2 v[106:107], v204, s[30:31] offset:96
	global_load_dwordx4 v[80:83], v206, s[28:29] offset:192
	global_load_dwordx2 v[32:33], v205, s[34:35] offset:128
	global_load_dwordx2 v[108:109], v204, s[30:31] offset:128
	global_load_dwordx4 v[84:87], v206, s[28:29] offset:256
	global_load_dwordx2 v[34:35], v205, s[34:35] offset:160
	global_load_dwordx2 v[110:111], v204, s[30:31] offset:160
	global_load_dwordx4 v[88:91], v206, s[28:29] offset:320
	global_load_dwordx2 v[36:37], v205, s[34:35] offset:192
	global_load_dwordx2 v[112:113], v204, s[30:31] offset:192
	global_load_dwordx4 v[92:95], v206, s[28:29] offset:384
	global_load_dwordx2 v[38:39], v205, s[34:35] offset:224
	global_load_dwordx2 v[114:115], v204, s[30:31] offset:224
	global_load_dwordx4 v[96:99], v206, s[28:29] offset:448
	global_load_dwordx2 v[40:41], v205, s[34:35] offset:256
	global_load_dwordx2 v[116:117], v204, s[30:31] offset:256
	global_load_dwordx4 v[132:135], v206, s[28:29] offset:512
	global_load_dwordx2 v[42:43], v205, s[34:35] offset:288
	global_load_dwordx2 v[118:119], v204, s[30:31] offset:288
	global_load_dwordx4 v[136:139], v206, s[28:29] offset:576
	global_load_dwordx2 v[44:45], v205, s[34:35] offset:320
	global_load_dwordx2 v[120:121], v204, s[30:31] offset:320
	global_load_dwordx4 v[144:147], v206, s[28:29] offset:640
	global_load_dwordx2 v[46:47], v205, s[34:35] offset:352
	global_load_dwordx2 v[122:123], v204, s[30:31] offset:352
	global_load_dwordx4 v[148:151], v206, s[28:29] offset:704
	global_load_dwordx2 v[48:49], v205, s[34:35] offset:384
	global_load_dwordx2 v[124:125], v204, s[30:31] offset:384
	global_load_dwordx4 v[152:155], v206, s[28:29] offset:768
	global_load_dwordx2 v[50:51], v205, s[34:35] offset:416
	global_load_dwordx2 v[126:127], v204, s[30:31] offset:416
	global_load_dwordx4 v[156:159], v206, s[28:29] offset:832
	global_load_dwordx2 v[52:53], v205, s[34:35] offset:448
	global_load_dwordx2 v[128:129], v204, s[30:31] offset:448
	global_load_dwordx4 v[160:163], v206, s[28:29] offset:896
	global_load_dwordx2 v[54:55], v205, s[34:35] offset:480
	global_load_dwordx2 v[130:131], v204, s[30:31] offset:480
	global_load_dwordx4 v[164:167], v206, s[28:29] offset:960
	s_waitcnt vmcnt(45)
	v_lshlrev_b32_e32 v12, 16, v24
	v_and_b32_e32 v13, 0xffff0000, v24
	v_lshlrev_b32_e32 v14, 16, v25
	v_and_b32_e32 v15, 0xffff0000, v25
	v_mul_f32_e32 v16, 0xbfb8aa3b, v12
	v_mul_f32_e32 v17, 0xbfb8aa3b, v13
	v_mul_f32_e32 v18, 0xbfb8aa3b, v14
	v_mul_f32_e32 v19, 0xbfb8aa3b, v15
	v_exp_f32_e32 v16, v16
	v_exp_f32_e32 v17, v17
	v_exp_f32_e32 v18, v18
	v_exp_f32_e32 v19, v19
	v_lshlrev_b32_e32 v20, 16, v100
	v_and_b32_e32 v21, 0xffff0000, v100
	v_lshlrev_b32_e32 v22, 16, v101
	v_and_b32_e32 v23, 0xffff0000, v101
	v_add_f32_e32 v16, 1.0, v16
	v_add_f32_e32 v17, 1.0, v17
	v_add_f32_e32 v18, 1.0, v18
	v_add_f32_e32 v19, 1.0, v19
	v_rcp_f32_e32 v16, v16
	v_rcp_f32_e32 v17, v17
	v_rcp_f32_e32 v18, v18
	v_rcp_f32_e32 v19, v19
	v_sub_f32_e32 v20, v20, v227
	v_sub_f32_e32 v21, v21, v227
	v_sub_f32_e32 v22, v22, v227
	v_sub_f32_e32 v23, v23, v227
	v_mul_f32_e32 v20, v20, v228
	v_mul_f32_e32 v21, v21, v228
	v_mul_f32_e32 v22, v22, v228
	v_mul_f32_e32 v23, v23, v228
	v_mul_f32_e32 v12, v12, v16
	v_mul_f32_e32 v13, v13, v17
	v_mul_f32_e32 v14, v14, v18
	v_mul_f32_e32 v15, v15, v19
	v_mul_f32_e32 v20, v20, v68
	v_mul_f32_e32 v21, v21, v69
	v_mul_f32_e32 v22, v22, v70
	v_mul_f32_e32 v23, v23, v71
	v_mul_f32_e32 v20, v20, v12
	v_mul_f32_e32 v21, v21, v13
	v_mul_f32_e32 v22, v22, v14
	v_mul_f32_e32 v23, v23, v15
	v_cvt_pk_bf16_f32 v20, v20, v21
	v_cvt_pk_bf16_f32 v21, v22, v23
	global_store_dwordx2 v204, v[20:21], s[30:31] offset:0
	s_waitcnt vmcnt(42)
	v_lshlrev_b32_e32 v12, 16, v26
	v_and_b32_e32 v13, 0xffff0000, v26
	v_lshlrev_b32_e32 v14, 16, v27
	v_and_b32_e32 v15, 0xffff0000, v27
	v_mul_f32_e32 v16, 0xbfb8aa3b, v12
	v_mul_f32_e32 v17, 0xbfb8aa3b, v13
	v_mul_f32_e32 v18, 0xbfb8aa3b, v14
	v_mul_f32_e32 v19, 0xbfb8aa3b, v15
	v_exp_f32_e32 v16, v16
	v_exp_f32_e32 v17, v17
	v_exp_f32_e32 v18, v18
	v_exp_f32_e32 v19, v19
	v_lshlrev_b32_e32 v20, 16, v102
	v_and_b32_e32 v21, 0xffff0000, v102
	v_lshlrev_b32_e32 v22, 16, v103
	v_and_b32_e32 v23, 0xffff0000, v103
	v_add_f32_e32 v16, 1.0, v16
	v_add_f32_e32 v17, 1.0, v17
	v_add_f32_e32 v18, 1.0, v18
	v_add_f32_e32 v19, 1.0, v19
	v_rcp_f32_e32 v16, v16
	v_rcp_f32_e32 v17, v17
	v_rcp_f32_e32 v18, v18
	v_rcp_f32_e32 v19, v19
	v_sub_f32_e32 v20, v20, v227
	v_sub_f32_e32 v21, v21, v227
	v_sub_f32_e32 v22, v22, v227
	v_sub_f32_e32 v23, v23, v227
	v_mul_f32_e32 v20, v20, v228
	v_mul_f32_e32 v21, v21, v228
	v_mul_f32_e32 v22, v22, v228
	v_mul_f32_e32 v23, v23, v228
	v_mul_f32_e32 v12, v12, v16
	v_mul_f32_e32 v13, v13, v17
	v_mul_f32_e32 v14, v14, v18
	v_mul_f32_e32 v15, v15, v19
	v_mul_f32_e32 v20, v20, v72
	v_mul_f32_e32 v21, v21, v73
	v_mul_f32_e32 v22, v22, v74
	v_mul_f32_e32 v23, v23, v75
	v_mul_f32_e32 v20, v20, v12
	v_mul_f32_e32 v21, v21, v13
	v_mul_f32_e32 v22, v22, v14
	v_mul_f32_e32 v23, v23, v15
	v_cvt_pk_bf16_f32 v20, v20, v21
	v_cvt_pk_bf16_f32 v21, v22, v23
	global_store_dwordx2 v204, v[20:21], s[30:31] offset:32
	s_waitcnt vmcnt(39)
	v_lshlrev_b32_e32 v12, 16, v28
	v_and_b32_e32 v13, 0xffff0000, v28
	v_lshlrev_b32_e32 v14, 16, v29
	v_and_b32_e32 v15, 0xffff0000, v29
	v_mul_f32_e32 v16, 0xbfb8aa3b, v12
	v_mul_f32_e32 v17, 0xbfb8aa3b, v13
	v_mul_f32_e32 v18, 0xbfb8aa3b, v14
	v_mul_f32_e32 v19, 0xbfb8aa3b, v15
	v_exp_f32_e32 v16, v16
	v_exp_f32_e32 v17, v17
	v_exp_f32_e32 v18, v18
	v_exp_f32_e32 v19, v19
	v_lshlrev_b32_e32 v20, 16, v104
	v_and_b32_e32 v21, 0xffff0000, v104
	v_lshlrev_b32_e32 v22, 16, v105
	v_and_b32_e32 v23, 0xffff0000, v105
	v_add_f32_e32 v16, 1.0, v16
	v_add_f32_e32 v17, 1.0, v17
	v_add_f32_e32 v18, 1.0, v18
	v_add_f32_e32 v19, 1.0, v19
	v_rcp_f32_e32 v16, v16
	v_rcp_f32_e32 v17, v17
	v_rcp_f32_e32 v18, v18
	v_rcp_f32_e32 v19, v19
	v_sub_f32_e32 v20, v20, v227
	v_sub_f32_e32 v21, v21, v227
	v_sub_f32_e32 v22, v22, v227
	v_sub_f32_e32 v23, v23, v227
	v_mul_f32_e32 v20, v20, v228
	v_mul_f32_e32 v21, v21, v228
	v_mul_f32_e32 v22, v22, v228
	v_mul_f32_e32 v23, v23, v228
	v_mul_f32_e32 v12, v12, v16
	v_mul_f32_e32 v13, v13, v17
	v_mul_f32_e32 v14, v14, v18
	v_mul_f32_e32 v15, v15, v19
	v_mul_f32_e32 v20, v20, v76
	v_mul_f32_e32 v21, v21, v77
	v_mul_f32_e32 v22, v22, v78
	v_mul_f32_e32 v23, v23, v79
	v_mul_f32_e32 v20, v20, v12
	v_mul_f32_e32 v21, v21, v13
	v_mul_f32_e32 v22, v22, v14
	v_mul_f32_e32 v23, v23, v15
	v_cvt_pk_bf16_f32 v20, v20, v21
	v_cvt_pk_bf16_f32 v21, v22, v23
	global_store_dwordx2 v204, v[20:21], s[30:31] offset:64
	s_waitcnt vmcnt(36)
	v_lshlrev_b32_e32 v12, 16, v30
	v_and_b32_e32 v13, 0xffff0000, v30
	v_lshlrev_b32_e32 v14, 16, v31
	v_and_b32_e32 v15, 0xffff0000, v31
	v_mul_f32_e32 v16, 0xbfb8aa3b, v12
	v_mul_f32_e32 v17, 0xbfb8aa3b, v13
	v_mul_f32_e32 v18, 0xbfb8aa3b, v14
	v_mul_f32_e32 v19, 0xbfb8aa3b, v15
	v_exp_f32_e32 v16, v16
	v_exp_f32_e32 v17, v17
	v_exp_f32_e32 v18, v18
	v_exp_f32_e32 v19, v19
	v_lshlrev_b32_e32 v20, 16, v106
	v_and_b32_e32 v21, 0xffff0000, v106
	v_lshlrev_b32_e32 v22, 16, v107
	v_and_b32_e32 v23, 0xffff0000, v107
	v_add_f32_e32 v16, 1.0, v16
	v_add_f32_e32 v17, 1.0, v17
	v_add_f32_e32 v18, 1.0, v18
	v_add_f32_e32 v19, 1.0, v19
	v_rcp_f32_e32 v16, v16
	v_rcp_f32_e32 v17, v17
	v_rcp_f32_e32 v18, v18
	v_rcp_f32_e32 v19, v19
	v_sub_f32_e32 v20, v20, v227
	v_sub_f32_e32 v21, v21, v227
	v_sub_f32_e32 v22, v22, v227
	v_sub_f32_e32 v23, v23, v227
	v_mul_f32_e32 v20, v20, v228
	v_mul_f32_e32 v21, v21, v228
	v_mul_f32_e32 v22, v22, v228
	v_mul_f32_e32 v23, v23, v228
	v_mul_f32_e32 v12, v12, v16
	v_mul_f32_e32 v13, v13, v17
	v_mul_f32_e32 v14, v14, v18
	v_mul_f32_e32 v15, v15, v19
	v_mul_f32_e32 v20, v20, v80
	v_mul_f32_e32 v21, v21, v81
	v_mul_f32_e32 v22, v22, v82
	v_mul_f32_e32 v23, v23, v83
	v_mul_f32_e32 v20, v20, v12
	v_mul_f32_e32 v21, v21, v13
	v_mul_f32_e32 v22, v22, v14
	v_mul_f32_e32 v23, v23, v15
	v_cvt_pk_bf16_f32 v20, v20, v21
	v_cvt_pk_bf16_f32 v21, v22, v23
	global_store_dwordx2 v204, v[20:21], s[30:31] offset:96
	s_waitcnt vmcnt(33)
	v_lshlrev_b32_e32 v12, 16, v32
	v_and_b32_e32 v13, 0xffff0000, v32
	v_lshlrev_b32_e32 v14, 16, v33
	v_and_b32_e32 v15, 0xffff0000, v33
	v_mul_f32_e32 v16, 0xbfb8aa3b, v12
	v_mul_f32_e32 v17, 0xbfb8aa3b, v13
	v_mul_f32_e32 v18, 0xbfb8aa3b, v14
	v_mul_f32_e32 v19, 0xbfb8aa3b, v15
	v_exp_f32_e32 v16, v16
	v_exp_f32_e32 v17, v17
	v_exp_f32_e32 v18, v18
	v_exp_f32_e32 v19, v19
	v_lshlrev_b32_e32 v20, 16, v108
	v_and_b32_e32 v21, 0xffff0000, v108
	v_lshlrev_b32_e32 v22, 16, v109
	v_and_b32_e32 v23, 0xffff0000, v109
	v_add_f32_e32 v16, 1.0, v16
	v_add_f32_e32 v17, 1.0, v17
	v_add_f32_e32 v18, 1.0, v18
	v_add_f32_e32 v19, 1.0, v19
	v_rcp_f32_e32 v16, v16
	v_rcp_f32_e32 v17, v17
	v_rcp_f32_e32 v18, v18
	v_rcp_f32_e32 v19, v19
	v_sub_f32_e32 v20, v20, v227
	v_sub_f32_e32 v21, v21, v227
	v_sub_f32_e32 v22, v22, v227
	v_sub_f32_e32 v23, v23, v227
	v_mul_f32_e32 v20, v20, v228
	v_mul_f32_e32 v21, v21, v228
	v_mul_f32_e32 v22, v22, v228
	v_mul_f32_e32 v23, v23, v228
	v_mul_f32_e32 v12, v12, v16
	v_mul_f32_e32 v13, v13, v17
	v_mul_f32_e32 v14, v14, v18
	v_mul_f32_e32 v15, v15, v19
	v_mul_f32_e32 v20, v20, v84
	v_mul_f32_e32 v21, v21, v85
	v_mul_f32_e32 v22, v22, v86
	v_mul_f32_e32 v23, v23, v87
	v_mul_f32_e32 v20, v20, v12
	v_mul_f32_e32 v21, v21, v13
	v_mul_f32_e32 v22, v22, v14
	v_mul_f32_e32 v23, v23, v15
	v_cvt_pk_bf16_f32 v20, v20, v21
	v_cvt_pk_bf16_f32 v21, v22, v23
	global_store_dwordx2 v204, v[20:21], s[30:31] offset:128
	s_waitcnt vmcnt(30)
	v_lshlrev_b32_e32 v12, 16, v34
	v_and_b32_e32 v13, 0xffff0000, v34
	v_lshlrev_b32_e32 v14, 16, v35
	v_and_b32_e32 v15, 0xffff0000, v35
	v_mul_f32_e32 v16, 0xbfb8aa3b, v12
	v_mul_f32_e32 v17, 0xbfb8aa3b, v13
	v_mul_f32_e32 v18, 0xbfb8aa3b, v14
	v_mul_f32_e32 v19, 0xbfb8aa3b, v15
	v_exp_f32_e32 v16, v16
	v_exp_f32_e32 v17, v17
	v_exp_f32_e32 v18, v18
	v_exp_f32_e32 v19, v19
	v_lshlrev_b32_e32 v20, 16, v110
	v_and_b32_e32 v21, 0xffff0000, v110
	v_lshlrev_b32_e32 v22, 16, v111
	v_and_b32_e32 v23, 0xffff0000, v111
	v_add_f32_e32 v16, 1.0, v16
	v_add_f32_e32 v17, 1.0, v17
	v_add_f32_e32 v18, 1.0, v18
	v_add_f32_e32 v19, 1.0, v19
	v_rcp_f32_e32 v16, v16
	v_rcp_f32_e32 v17, v17
	v_rcp_f32_e32 v18, v18
	v_rcp_f32_e32 v19, v19
	v_sub_f32_e32 v20, v20, v227
	v_sub_f32_e32 v21, v21, v227
	v_sub_f32_e32 v22, v22, v227
	v_sub_f32_e32 v23, v23, v227
	v_mul_f32_e32 v20, v20, v228
	v_mul_f32_e32 v21, v21, v228
	v_mul_f32_e32 v22, v22, v228
	v_mul_f32_e32 v23, v23, v228
	v_mul_f32_e32 v12, v12, v16
	v_mul_f32_e32 v13, v13, v17
	v_mul_f32_e32 v14, v14, v18
	v_mul_f32_e32 v15, v15, v19
	v_mul_f32_e32 v20, v20, v88
	v_mul_f32_e32 v21, v21, v89
	v_mul_f32_e32 v22, v22, v90
	v_mul_f32_e32 v23, v23, v91
	v_mul_f32_e32 v20, v20, v12
	v_mul_f32_e32 v21, v21, v13
	v_mul_f32_e32 v22, v22, v14
	v_mul_f32_e32 v23, v23, v15
	v_cvt_pk_bf16_f32 v20, v20, v21
	v_cvt_pk_bf16_f32 v21, v22, v23
	global_store_dwordx2 v204, v[20:21], s[30:31] offset:160
	s_waitcnt vmcnt(27)
	v_lshlrev_b32_e32 v12, 16, v36
	v_and_b32_e32 v13, 0xffff0000, v36
	v_lshlrev_b32_e32 v14, 16, v37
	v_and_b32_e32 v15, 0xffff0000, v37
	v_mul_f32_e32 v16, 0xbfb8aa3b, v12
	v_mul_f32_e32 v17, 0xbfb8aa3b, v13
	v_mul_f32_e32 v18, 0xbfb8aa3b, v14
	v_mul_f32_e32 v19, 0xbfb8aa3b, v15
	v_exp_f32_e32 v16, v16
	v_exp_f32_e32 v17, v17
	v_exp_f32_e32 v18, v18
	v_exp_f32_e32 v19, v19
	v_lshlrev_b32_e32 v20, 16, v112
	v_and_b32_e32 v21, 0xffff0000, v112
	v_lshlrev_b32_e32 v22, 16, v113
	v_and_b32_e32 v23, 0xffff0000, v113
	v_add_f32_e32 v16, 1.0, v16
	v_add_f32_e32 v17, 1.0, v17
	v_add_f32_e32 v18, 1.0, v18
	v_add_f32_e32 v19, 1.0, v19
	v_rcp_f32_e32 v16, v16
	v_rcp_f32_e32 v17, v17
	v_rcp_f32_e32 v18, v18
	v_rcp_f32_e32 v19, v19
	v_sub_f32_e32 v20, v20, v227
	v_sub_f32_e32 v21, v21, v227
	v_sub_f32_e32 v22, v22, v227
	v_sub_f32_e32 v23, v23, v227
	v_mul_f32_e32 v20, v20, v228
	v_mul_f32_e32 v21, v21, v228
	v_mul_f32_e32 v22, v22, v228
	v_mul_f32_e32 v23, v23, v228
	v_mul_f32_e32 v12, v12, v16
	v_mul_f32_e32 v13, v13, v17
	v_mul_f32_e32 v14, v14, v18
	v_mul_f32_e32 v15, v15, v19
	v_mul_f32_e32 v20, v20, v92
	v_mul_f32_e32 v21, v21, v93
	v_mul_f32_e32 v22, v22, v94
	v_mul_f32_e32 v23, v23, v95
	v_mul_f32_e32 v20, v20, v12
	v_mul_f32_e32 v21, v21, v13
	v_mul_f32_e32 v22, v22, v14
	v_mul_f32_e32 v23, v23, v15
	v_cvt_pk_bf16_f32 v20, v20, v21
	v_cvt_pk_bf16_f32 v21, v22, v23
	global_store_dwordx2 v204, v[20:21], s[30:31] offset:192
	s_waitcnt vmcnt(24)
	v_lshlrev_b32_e32 v12, 16, v38
	v_and_b32_e32 v13, 0xffff0000, v38
	v_lshlrev_b32_e32 v14, 16, v39
	v_and_b32_e32 v15, 0xffff0000, v39
	v_mul_f32_e32 v16, 0xbfb8aa3b, v12
	v_mul_f32_e32 v17, 0xbfb8aa3b, v13
	v_mul_f32_e32 v18, 0xbfb8aa3b, v14
	v_mul_f32_e32 v19, 0xbfb8aa3b, v15
	v_exp_f32_e32 v16, v16
	v_exp_f32_e32 v17, v17
	v_exp_f32_e32 v18, v18
	v_exp_f32_e32 v19, v19
	v_lshlrev_b32_e32 v20, 16, v114
	v_and_b32_e32 v21, 0xffff0000, v114
	v_lshlrev_b32_e32 v22, 16, v115
	v_and_b32_e32 v23, 0xffff0000, v115
	v_add_f32_e32 v16, 1.0, v16
	v_add_f32_e32 v17, 1.0, v17
	v_add_f32_e32 v18, 1.0, v18
	v_add_f32_e32 v19, 1.0, v19
	v_rcp_f32_e32 v16, v16
	v_rcp_f32_e32 v17, v17
	v_rcp_f32_e32 v18, v18
	v_rcp_f32_e32 v19, v19
	v_sub_f32_e32 v20, v20, v227
	v_sub_f32_e32 v21, v21, v227
	v_sub_f32_e32 v22, v22, v227
	v_sub_f32_e32 v23, v23, v227
	v_mul_f32_e32 v20, v20, v228
	v_mul_f32_e32 v21, v21, v228
	v_mul_f32_e32 v22, v22, v228
	v_mul_f32_e32 v23, v23, v228
	v_mul_f32_e32 v12, v12, v16
	v_mul_f32_e32 v13, v13, v17
	v_mul_f32_e32 v14, v14, v18
	v_mul_f32_e32 v15, v15, v19
	v_mul_f32_e32 v20, v20, v96
	v_mul_f32_e32 v21, v21, v97
	v_mul_f32_e32 v22, v22, v98
	v_mul_f32_e32 v23, v23, v99
	v_mul_f32_e32 v20, v20, v12
	v_mul_f32_e32 v21, v21, v13
	v_mul_f32_e32 v22, v22, v14
	v_mul_f32_e32 v23, v23, v15
	v_cvt_pk_bf16_f32 v20, v20, v21
	v_cvt_pk_bf16_f32 v21, v22, v23
	global_store_dwordx2 v204, v[20:21], s[30:31] offset:224
	global_load_dwordx2 v[24:25], v205, s[34:35] offset:512
	global_load_dwordx2 v[100:101], v204, s[30:31] offset:512
	global_load_dwordx4 v[68:71], v206, s[28:29] offset:1024
	global_load_dwordx2 v[26:27], v205, s[34:35] offset:544
	global_load_dwordx2 v[102:103], v204, s[30:31] offset:544
	global_load_dwordx4 v[72:75], v206, s[28:29] offset:1088
	global_load_dwordx2 v[28:29], v205, s[34:35] offset:576
	global_load_dwordx2 v[104:105], v204, s[30:31] offset:576
	global_load_dwordx4 v[76:79], v206, s[28:29] offset:1152
	global_load_dwordx2 v[30:31], v205, s[34:35] offset:608
	global_load_dwordx2 v[106:107], v204, s[30:31] offset:608
	global_load_dwordx4 v[80:83], v206, s[28:29] offset:1216
	global_load_dwordx2 v[32:33], v205, s[34:35] offset:640
	global_load_dwordx2 v[108:109], v204, s[30:31] offset:640
	global_load_dwordx4 v[84:87], v206, s[28:29] offset:1280
	global_load_dwordx2 v[34:35], v205, s[34:35] offset:672
	global_load_dwordx2 v[110:111], v204, s[30:31] offset:672
	global_load_dwordx4 v[88:91], v206, s[28:29] offset:1344
	global_load_dwordx2 v[36:37], v205, s[34:35] offset:704
	global_load_dwordx2 v[112:113], v204, s[30:31] offset:704
	global_load_dwordx4 v[92:95], v206, s[28:29] offset:1408
	global_load_dwordx2 v[38:39], v205, s[34:35] offset:736
	global_load_dwordx2 v[114:115], v204, s[30:31] offset:736
	global_load_dwordx4 v[96:99], v206, s[28:29] offset:1472
	s_waitcnt vmcnt(45)
	v_lshlrev_b32_e32 v12, 16, v40
	v_and_b32_e32 v13, 0xffff0000, v40
	v_lshlrev_b32_e32 v14, 16, v41
	v_and_b32_e32 v15, 0xffff0000, v41
	v_mul_f32_e32 v16, 0xbfb8aa3b, v12
	v_mul_f32_e32 v17, 0xbfb8aa3b, v13
	v_mul_f32_e32 v18, 0xbfb8aa3b, v14
	v_mul_f32_e32 v19, 0xbfb8aa3b, v15
	v_exp_f32_e32 v16, v16
	v_exp_f32_e32 v17, v17
	v_exp_f32_e32 v18, v18
	v_exp_f32_e32 v19, v19
	v_lshlrev_b32_e32 v20, 16, v116
	v_and_b32_e32 v21, 0xffff0000, v116
	v_lshlrev_b32_e32 v22, 16, v117
	v_and_b32_e32 v23, 0xffff0000, v117
	v_add_f32_e32 v16, 1.0, v16
	v_add_f32_e32 v17, 1.0, v17
	v_add_f32_e32 v18, 1.0, v18
	v_add_f32_e32 v19, 1.0, v19
	v_rcp_f32_e32 v16, v16
	v_rcp_f32_e32 v17, v17
	v_rcp_f32_e32 v18, v18
	v_rcp_f32_e32 v19, v19
	v_sub_f32_e32 v20, v20, v227
	v_sub_f32_e32 v21, v21, v227
	v_sub_f32_e32 v22, v22, v227
	v_sub_f32_e32 v23, v23, v227
	v_mul_f32_e32 v20, v20, v228
	v_mul_f32_e32 v21, v21, v228
	v_mul_f32_e32 v22, v22, v228
	v_mul_f32_e32 v23, v23, v228
	v_mul_f32_e32 v12, v12, v16
	v_mul_f32_e32 v13, v13, v17
	v_mul_f32_e32 v14, v14, v18
	v_mul_f32_e32 v15, v15, v19
	v_mul_f32_e32 v20, v20, v132
	v_mul_f32_e32 v21, v21, v133
	v_mul_f32_e32 v22, v22, v134
	v_mul_f32_e32 v23, v23, v135
	v_mul_f32_e32 v20, v20, v12
	v_mul_f32_e32 v21, v21, v13
	v_mul_f32_e32 v22, v22, v14
	v_mul_f32_e32 v23, v23, v15
	v_cvt_pk_bf16_f32 v20, v20, v21
	v_cvt_pk_bf16_f32 v21, v22, v23
	global_store_dwordx2 v204, v[20:21], s[30:31] offset:256
	s_waitcnt vmcnt(42)
	v_lshlrev_b32_e32 v12, 16, v42
	v_and_b32_e32 v13, 0xffff0000, v42
	v_lshlrev_b32_e32 v14, 16, v43
	v_and_b32_e32 v15, 0xffff0000, v43
	v_mul_f32_e32 v16, 0xbfb8aa3b, v12
	v_mul_f32_e32 v17, 0xbfb8aa3b, v13
	v_mul_f32_e32 v18, 0xbfb8aa3b, v14
	v_mul_f32_e32 v19, 0xbfb8aa3b, v15
	v_exp_f32_e32 v16, v16
	v_exp_f32_e32 v17, v17
	v_exp_f32_e32 v18, v18
	v_exp_f32_e32 v19, v19
	v_lshlrev_b32_e32 v20, 16, v118
	v_and_b32_e32 v21, 0xffff0000, v118
	v_lshlrev_b32_e32 v22, 16, v119
	v_and_b32_e32 v23, 0xffff0000, v119
	v_add_f32_e32 v16, 1.0, v16
	v_add_f32_e32 v17, 1.0, v17
	v_add_f32_e32 v18, 1.0, v18
	v_add_f32_e32 v19, 1.0, v19
	v_rcp_f32_e32 v16, v16
	v_rcp_f32_e32 v17, v17
	v_rcp_f32_e32 v18, v18
	v_rcp_f32_e32 v19, v19
	v_sub_f32_e32 v20, v20, v227
	v_sub_f32_e32 v21, v21, v227
	v_sub_f32_e32 v22, v22, v227
	v_sub_f32_e32 v23, v23, v227
	v_mul_f32_e32 v20, v20, v228
	v_mul_f32_e32 v21, v21, v228
	v_mul_f32_e32 v22, v22, v228
	v_mul_f32_e32 v23, v23, v228
	v_mul_f32_e32 v12, v12, v16
	v_mul_f32_e32 v13, v13, v17
	v_mul_f32_e32 v14, v14, v18
	v_mul_f32_e32 v15, v15, v19
	v_mul_f32_e32 v20, v20, v136
	v_mul_f32_e32 v21, v21, v137
	v_mul_f32_e32 v22, v22, v138
	v_mul_f32_e32 v23, v23, v139
	v_mul_f32_e32 v20, v20, v12
	v_mul_f32_e32 v21, v21, v13
	v_mul_f32_e32 v22, v22, v14
	v_mul_f32_e32 v23, v23, v15
	v_cvt_pk_bf16_f32 v20, v20, v21
	v_cvt_pk_bf16_f32 v21, v22, v23
	global_store_dwordx2 v204, v[20:21], s[30:31] offset:288
	s_waitcnt vmcnt(39)
	v_lshlrev_b32_e32 v12, 16, v44
	v_and_b32_e32 v13, 0xffff0000, v44
	v_lshlrev_b32_e32 v14, 16, v45
	v_and_b32_e32 v15, 0xffff0000, v45
	v_mul_f32_e32 v16, 0xbfb8aa3b, v12
	v_mul_f32_e32 v17, 0xbfb8aa3b, v13
	v_mul_f32_e32 v18, 0xbfb8aa3b, v14
	v_mul_f32_e32 v19, 0xbfb8aa3b, v15
	v_exp_f32_e32 v16, v16
	v_exp_f32_e32 v17, v17
	v_exp_f32_e32 v18, v18
	v_exp_f32_e32 v19, v19
	v_lshlrev_b32_e32 v20, 16, v120
	v_and_b32_e32 v21, 0xffff0000, v120
	v_lshlrev_b32_e32 v22, 16, v121
	v_and_b32_e32 v23, 0xffff0000, v121
	v_add_f32_e32 v16, 1.0, v16
	v_add_f32_e32 v17, 1.0, v17
	v_add_f32_e32 v18, 1.0, v18
	v_add_f32_e32 v19, 1.0, v19
	v_rcp_f32_e32 v16, v16
	v_rcp_f32_e32 v17, v17
	v_rcp_f32_e32 v18, v18
	v_rcp_f32_e32 v19, v19
	v_sub_f32_e32 v20, v20, v227
	v_sub_f32_e32 v21, v21, v227
	v_sub_f32_e32 v22, v22, v227
	v_sub_f32_e32 v23, v23, v227
	v_mul_f32_e32 v20, v20, v228
	v_mul_f32_e32 v21, v21, v228
	v_mul_f32_e32 v22, v22, v228
	v_mul_f32_e32 v23, v23, v228
	v_mul_f32_e32 v12, v12, v16
	v_mul_f32_e32 v13, v13, v17
	v_mul_f32_e32 v14, v14, v18
	v_mul_f32_e32 v15, v15, v19
	v_mul_f32_e32 v20, v20, v144
	v_mul_f32_e32 v21, v21, v145
	v_mul_f32_e32 v22, v22, v146
	v_mul_f32_e32 v23, v23, v147
	v_mul_f32_e32 v20, v20, v12
	v_mul_f32_e32 v21, v21, v13
	v_mul_f32_e32 v22, v22, v14
	v_mul_f32_e32 v23, v23, v15
	v_cvt_pk_bf16_f32 v20, v20, v21
	v_cvt_pk_bf16_f32 v21, v22, v23
	global_store_dwordx2 v204, v[20:21], s[30:31] offset:320
	s_waitcnt vmcnt(36)
	v_lshlrev_b32_e32 v12, 16, v46
	v_and_b32_e32 v13, 0xffff0000, v46
	v_lshlrev_b32_e32 v14, 16, v47
	v_and_b32_e32 v15, 0xffff0000, v47
	v_mul_f32_e32 v16, 0xbfb8aa3b, v12
	v_mul_f32_e32 v17, 0xbfb8aa3b, v13
	v_mul_f32_e32 v18, 0xbfb8aa3b, v14
	v_mul_f32_e32 v19, 0xbfb8aa3b, v15
	v_exp_f32_e32 v16, v16
	v_exp_f32_e32 v17, v17
	v_exp_f32_e32 v18, v18
	v_exp_f32_e32 v19, v19
	v_lshlrev_b32_e32 v20, 16, v122
	v_and_b32_e32 v21, 0xffff0000, v122
	v_lshlrev_b32_e32 v22, 16, v123
	v_and_b32_e32 v23, 0xffff0000, v123
	v_add_f32_e32 v16, 1.0, v16
	v_add_f32_e32 v17, 1.0, v17
	v_add_f32_e32 v18, 1.0, v18
	v_add_f32_e32 v19, 1.0, v19
	v_rcp_f32_e32 v16, v16
	v_rcp_f32_e32 v17, v17
	v_rcp_f32_e32 v18, v18
	v_rcp_f32_e32 v19, v19
	v_sub_f32_e32 v20, v20, v227
	v_sub_f32_e32 v21, v21, v227
	v_sub_f32_e32 v22, v22, v227
	v_sub_f32_e32 v23, v23, v227
	v_mul_f32_e32 v20, v20, v228
	v_mul_f32_e32 v21, v21, v228
	v_mul_f32_e32 v22, v22, v228
	v_mul_f32_e32 v23, v23, v228
	v_mul_f32_e32 v12, v12, v16
	v_mul_f32_e32 v13, v13, v17
	v_mul_f32_e32 v14, v14, v18
	v_mul_f32_e32 v15, v15, v19
	v_mul_f32_e32 v20, v20, v148
	v_mul_f32_e32 v21, v21, v149
	v_mul_f32_e32 v22, v22, v150
	v_mul_f32_e32 v23, v23, v151
	v_mul_f32_e32 v20, v20, v12
	v_mul_f32_e32 v21, v21, v13
	v_mul_f32_e32 v22, v22, v14
	v_mul_f32_e32 v23, v23, v15
	v_cvt_pk_bf16_f32 v20, v20, v21
	v_cvt_pk_bf16_f32 v21, v22, v23
	global_store_dwordx2 v204, v[20:21], s[30:31] offset:352
	s_waitcnt vmcnt(33)
	v_lshlrev_b32_e32 v12, 16, v48
	v_and_b32_e32 v13, 0xffff0000, v48
	v_lshlrev_b32_e32 v14, 16, v49
	v_and_b32_e32 v15, 0xffff0000, v49
	v_mul_f32_e32 v16, 0xbfb8aa3b, v12
	v_mul_f32_e32 v17, 0xbfb8aa3b, v13
	v_mul_f32_e32 v18, 0xbfb8aa3b, v14
	v_mul_f32_e32 v19, 0xbfb8aa3b, v15
	v_exp_f32_e32 v16, v16
	v_exp_f32_e32 v17, v17
	v_exp_f32_e32 v18, v18
	v_exp_f32_e32 v19, v19
	v_lshlrev_b32_e32 v20, 16, v124
	v_and_b32_e32 v21, 0xffff0000, v124
	v_lshlrev_b32_e32 v22, 16, v125
	v_and_b32_e32 v23, 0xffff0000, v125
	v_add_f32_e32 v16, 1.0, v16
	v_add_f32_e32 v17, 1.0, v17
	v_add_f32_e32 v18, 1.0, v18
	v_add_f32_e32 v19, 1.0, v19
	v_rcp_f32_e32 v16, v16
	v_rcp_f32_e32 v17, v17
	v_rcp_f32_e32 v18, v18
	v_rcp_f32_e32 v19, v19
	v_sub_f32_e32 v20, v20, v227
	v_sub_f32_e32 v21, v21, v227
	v_sub_f32_e32 v22, v22, v227
	v_sub_f32_e32 v23, v23, v227
	v_mul_f32_e32 v20, v20, v228
	v_mul_f32_e32 v21, v21, v228
	v_mul_f32_e32 v22, v22, v228
	v_mul_f32_e32 v23, v23, v228
	v_mul_f32_e32 v12, v12, v16
	v_mul_f32_e32 v13, v13, v17
	v_mul_f32_e32 v14, v14, v18
	v_mul_f32_e32 v15, v15, v19
	v_mul_f32_e32 v20, v20, v152
	v_mul_f32_e32 v21, v21, v153
	v_mul_f32_e32 v22, v22, v154
	v_mul_f32_e32 v23, v23, v155
	v_mul_f32_e32 v20, v20, v12
	v_mul_f32_e32 v21, v21, v13
	v_mul_f32_e32 v22, v22, v14
	v_mul_f32_e32 v23, v23, v15
	v_cvt_pk_bf16_f32 v20, v20, v21
	v_cvt_pk_bf16_f32 v21, v22, v23
	global_store_dwordx2 v204, v[20:21], s[30:31] offset:384
	s_waitcnt vmcnt(30)
	v_lshlrev_b32_e32 v12, 16, v50
	v_and_b32_e32 v13, 0xffff0000, v50
	v_lshlrev_b32_e32 v14, 16, v51
	v_and_b32_e32 v15, 0xffff0000, v51
	v_mul_f32_e32 v16, 0xbfb8aa3b, v12
	v_mul_f32_e32 v17, 0xbfb8aa3b, v13
	v_mul_f32_e32 v18, 0xbfb8aa3b, v14
	v_mul_f32_e32 v19, 0xbfb8aa3b, v15
	v_exp_f32_e32 v16, v16
	v_exp_f32_e32 v17, v17
	v_exp_f32_e32 v18, v18
	v_exp_f32_e32 v19, v19
	v_lshlrev_b32_e32 v20, 16, v126
	v_and_b32_e32 v21, 0xffff0000, v126
	v_lshlrev_b32_e32 v22, 16, v127
	v_and_b32_e32 v23, 0xffff0000, v127
	v_add_f32_e32 v16, 1.0, v16
	v_add_f32_e32 v17, 1.0, v17
	v_add_f32_e32 v18, 1.0, v18
	v_add_f32_e32 v19, 1.0, v19
	v_rcp_f32_e32 v16, v16
	v_rcp_f32_e32 v17, v17
	v_rcp_f32_e32 v18, v18
	v_rcp_f32_e32 v19, v19
	v_sub_f32_e32 v20, v20, v227
	v_sub_f32_e32 v21, v21, v227
	v_sub_f32_e32 v22, v22, v227
	v_sub_f32_e32 v23, v23, v227
	v_mul_f32_e32 v20, v20, v228
	v_mul_f32_e32 v21, v21, v228
	v_mul_f32_e32 v22, v22, v228
	v_mul_f32_e32 v23, v23, v228
	v_mul_f32_e32 v12, v12, v16
	v_mul_f32_e32 v13, v13, v17
	v_mul_f32_e32 v14, v14, v18
	v_mul_f32_e32 v15, v15, v19
	v_mul_f32_e32 v20, v20, v156
	v_mul_f32_e32 v21, v21, v157
	v_mul_f32_e32 v22, v22, v158
	v_mul_f32_e32 v23, v23, v159
	v_mul_f32_e32 v20, v20, v12
	v_mul_f32_e32 v21, v21, v13
	v_mul_f32_e32 v22, v22, v14
	v_mul_f32_e32 v23, v23, v15
	v_cvt_pk_bf16_f32 v20, v20, v21
	v_cvt_pk_bf16_f32 v21, v22, v23
	global_store_dwordx2 v204, v[20:21], s[30:31] offset:416
	s_waitcnt vmcnt(27)
	v_lshlrev_b32_e32 v12, 16, v52
	v_and_b32_e32 v13, 0xffff0000, v52
	v_lshlrev_b32_e32 v14, 16, v53
	v_and_b32_e32 v15, 0xffff0000, v53
	v_mul_f32_e32 v16, 0xbfb8aa3b, v12
	v_mul_f32_e32 v17, 0xbfb8aa3b, v13
	v_mul_f32_e32 v18, 0xbfb8aa3b, v14
	v_mul_f32_e32 v19, 0xbfb8aa3b, v15
	v_exp_f32_e32 v16, v16
	v_exp_f32_e32 v17, v17
	v_exp_f32_e32 v18, v18
	v_exp_f32_e32 v19, v19
	v_lshlrev_b32_e32 v20, 16, v128
	v_and_b32_e32 v21, 0xffff0000, v128
	v_lshlrev_b32_e32 v22, 16, v129
	v_and_b32_e32 v23, 0xffff0000, v129
	v_add_f32_e32 v16, 1.0, v16
	v_add_f32_e32 v17, 1.0, v17
	v_add_f32_e32 v18, 1.0, v18
	v_add_f32_e32 v19, 1.0, v19
	v_rcp_f32_e32 v16, v16
	v_rcp_f32_e32 v17, v17
	v_rcp_f32_e32 v18, v18
	v_rcp_f32_e32 v19, v19
	v_sub_f32_e32 v20, v20, v227
	v_sub_f32_e32 v21, v21, v227
	v_sub_f32_e32 v22, v22, v227
	v_sub_f32_e32 v23, v23, v227
	v_mul_f32_e32 v20, v20, v228
	v_mul_f32_e32 v21, v21, v228
	v_mul_f32_e32 v22, v22, v228
	v_mul_f32_e32 v23, v23, v228
	v_mul_f32_e32 v12, v12, v16
	v_mul_f32_e32 v13, v13, v17
	v_mul_f32_e32 v14, v14, v18
	v_mul_f32_e32 v15, v15, v19
	v_mul_f32_e32 v20, v20, v160
	v_mul_f32_e32 v21, v21, v161
	v_mul_f32_e32 v22, v22, v162
	v_mul_f32_e32 v23, v23, v163
	v_mul_f32_e32 v20, v20, v12
	v_mul_f32_e32 v21, v21, v13
	v_mul_f32_e32 v22, v22, v14
	v_mul_f32_e32 v23, v23, v15
	v_cvt_pk_bf16_f32 v20, v20, v21
	v_cvt_pk_bf16_f32 v21, v22, v23
	global_store_dwordx2 v204, v[20:21], s[30:31] offset:448
	s_waitcnt vmcnt(24)
	v_lshlrev_b32_e32 v12, 16, v54
	v_and_b32_e32 v13, 0xffff0000, v54
	v_lshlrev_b32_e32 v14, 16, v55
	v_and_b32_e32 v15, 0xffff0000, v55
	v_mul_f32_e32 v16, 0xbfb8aa3b, v12
	v_mul_f32_e32 v17, 0xbfb8aa3b, v13
	v_mul_f32_e32 v18, 0xbfb8aa3b, v14
	v_mul_f32_e32 v19, 0xbfb8aa3b, v15
	v_exp_f32_e32 v16, v16
	v_exp_f32_e32 v17, v17
	v_exp_f32_e32 v18, v18
	v_exp_f32_e32 v19, v19
	v_lshlrev_b32_e32 v20, 16, v130
	v_and_b32_e32 v21, 0xffff0000, v130
	v_lshlrev_b32_e32 v22, 16, v131
	v_and_b32_e32 v23, 0xffff0000, v131
	v_add_f32_e32 v16, 1.0, v16
	v_add_f32_e32 v17, 1.0, v17
	v_add_f32_e32 v18, 1.0, v18
	v_add_f32_e32 v19, 1.0, v19
	v_rcp_f32_e32 v16, v16
	v_rcp_f32_e32 v17, v17
	v_rcp_f32_e32 v18, v18
	v_rcp_f32_e32 v19, v19
	v_sub_f32_e32 v20, v20, v227
	v_sub_f32_e32 v21, v21, v227
	v_sub_f32_e32 v22, v22, v227
	v_sub_f32_e32 v23, v23, v227
	v_mul_f32_e32 v20, v20, v228
	v_mul_f32_e32 v21, v21, v228
	v_mul_f32_e32 v22, v22, v228
	v_mul_f32_e32 v23, v23, v228
	v_mul_f32_e32 v12, v12, v16
	v_mul_f32_e32 v13, v13, v17
	v_mul_f32_e32 v14, v14, v18
	v_mul_f32_e32 v15, v15, v19
	v_mul_f32_e32 v20, v20, v164
	v_mul_f32_e32 v21, v21, v165
	v_mul_f32_e32 v22, v22, v166
	v_mul_f32_e32 v23, v23, v167
	v_mul_f32_e32 v20, v20, v12
	v_mul_f32_e32 v21, v21, v13
	v_mul_f32_e32 v22, v22, v14
	v_mul_f32_e32 v23, v23, v15
	v_cvt_pk_bf16_f32 v20, v20, v21
	v_cvt_pk_bf16_f32 v21, v22, v23
	global_store_dwordx2 v204, v[20:21], s[30:31] offset:480
	global_load_dwordx2 v[40:41], v205, s[34:35] offset:768
	global_load_dwordx2 v[116:117], v204, s[30:31] offset:768
	global_load_dwordx4 v[132:135], v206, s[28:29] offset:1536
	global_load_dwordx2 v[42:43], v205, s[34:35] offset:800
	global_load_dwordx2 v[118:119], v204, s[30:31] offset:800
	global_load_dwordx4 v[136:139], v206, s[28:29] offset:1600
	global_load_dwordx2 v[44:45], v205, s[34:35] offset:832
	global_load_dwordx2 v[120:121], v204, s[30:31] offset:832
	global_load_dwordx4 v[144:147], v206, s[28:29] offset:1664
	global_load_dwordx2 v[46:47], v205, s[34:35] offset:864
	global_load_dwordx2 v[122:123], v204, s[30:31] offset:864
	global_load_dwordx4 v[148:151], v206, s[28:29] offset:1728
	global_load_dwordx2 v[48:49], v205, s[34:35] offset:896
	global_load_dwordx2 v[124:125], v204, s[30:31] offset:896
	global_load_dwordx4 v[152:155], v206, s[28:29] offset:1792
	global_load_dwordx2 v[50:51], v205, s[34:35] offset:928
	global_load_dwordx2 v[126:127], v204, s[30:31] offset:928
	global_load_dwordx4 v[156:159], v206, s[28:29] offset:1856
	global_load_dwordx2 v[52:53], v205, s[34:35] offset:960
	global_load_dwordx2 v[128:129], v204, s[30:31] offset:960
	global_load_dwordx4 v[160:163], v206, s[28:29] offset:1920
	global_load_dwordx2 v[54:55], v205, s[34:35] offset:992
	global_load_dwordx2 v[130:131], v204, s[30:31] offset:992
	global_load_dwordx4 v[164:167], v206, s[28:29] offset:1984
	s_waitcnt vmcnt(45)
	v_lshlrev_b32_e32 v12, 16, v24
	v_and_b32_e32 v13, 0xffff0000, v24
	v_lshlrev_b32_e32 v14, 16, v25
	v_and_b32_e32 v15, 0xffff0000, v25
	v_mul_f32_e32 v16, 0xbfb8aa3b, v12
	v_mul_f32_e32 v17, 0xbfb8aa3b, v13
	v_mul_f32_e32 v18, 0xbfb8aa3b, v14
	v_mul_f32_e32 v19, 0xbfb8aa3b, v15
	v_exp_f32_e32 v16, v16
	v_exp_f32_e32 v17, v17
	v_exp_f32_e32 v18, v18
	v_exp_f32_e32 v19, v19
	v_lshlrev_b32_e32 v20, 16, v100
	v_and_b32_e32 v21, 0xffff0000, v100
	v_lshlrev_b32_e32 v22, 16, v101
	v_and_b32_e32 v23, 0xffff0000, v101
	v_add_f32_e32 v16, 1.0, v16
	v_add_f32_e32 v17, 1.0, v17
	v_add_f32_e32 v18, 1.0, v18
	v_add_f32_e32 v19, 1.0, v19
	v_rcp_f32_e32 v16, v16
	v_rcp_f32_e32 v17, v17
	v_rcp_f32_e32 v18, v18
	v_rcp_f32_e32 v19, v19
	v_sub_f32_e32 v20, v20, v227
	v_sub_f32_e32 v21, v21, v227
	v_sub_f32_e32 v22, v22, v227
	v_sub_f32_e32 v23, v23, v227
	v_mul_f32_e32 v20, v20, v228
	v_mul_f32_e32 v21, v21, v228
	v_mul_f32_e32 v22, v22, v228
	v_mul_f32_e32 v23, v23, v228
	v_mul_f32_e32 v12, v12, v16
	v_mul_f32_e32 v13, v13, v17
	v_mul_f32_e32 v14, v14, v18
	v_mul_f32_e32 v15, v15, v19
	v_mul_f32_e32 v20, v20, v68
	v_mul_f32_e32 v21, v21, v69
	v_mul_f32_e32 v22, v22, v70
	v_mul_f32_e32 v23, v23, v71
	v_mul_f32_e32 v20, v20, v12
	v_mul_f32_e32 v21, v21, v13
	v_mul_f32_e32 v22, v22, v14
	v_mul_f32_e32 v23, v23, v15
	v_cvt_pk_bf16_f32 v20, v20, v21
	v_cvt_pk_bf16_f32 v21, v22, v23
	global_store_dwordx2 v204, v[20:21], s[30:31] offset:512
	s_waitcnt vmcnt(42)
	v_lshlrev_b32_e32 v12, 16, v26
	v_and_b32_e32 v13, 0xffff0000, v26
	v_lshlrev_b32_e32 v14, 16, v27
	v_and_b32_e32 v15, 0xffff0000, v27
	v_mul_f32_e32 v16, 0xbfb8aa3b, v12
	v_mul_f32_e32 v17, 0xbfb8aa3b, v13
	v_mul_f32_e32 v18, 0xbfb8aa3b, v14
	v_mul_f32_e32 v19, 0xbfb8aa3b, v15
	v_exp_f32_e32 v16, v16
	v_exp_f32_e32 v17, v17
	v_exp_f32_e32 v18, v18
	v_exp_f32_e32 v19, v19
	v_lshlrev_b32_e32 v20, 16, v102
	v_and_b32_e32 v21, 0xffff0000, v102
	v_lshlrev_b32_e32 v22, 16, v103
	v_and_b32_e32 v23, 0xffff0000, v103
	v_add_f32_e32 v16, 1.0, v16
	v_add_f32_e32 v17, 1.0, v17
	v_add_f32_e32 v18, 1.0, v18
	v_add_f32_e32 v19, 1.0, v19
	v_rcp_f32_e32 v16, v16
	v_rcp_f32_e32 v17, v17
	v_rcp_f32_e32 v18, v18
	v_rcp_f32_e32 v19, v19
	v_sub_f32_e32 v20, v20, v227
	v_sub_f32_e32 v21, v21, v227
	v_sub_f32_e32 v22, v22, v227
	v_sub_f32_e32 v23, v23, v227
	v_mul_f32_e32 v20, v20, v228
	v_mul_f32_e32 v21, v21, v228
	v_mul_f32_e32 v22, v22, v228
	v_mul_f32_e32 v23, v23, v228
	v_mul_f32_e32 v12, v12, v16
	v_mul_f32_e32 v13, v13, v17
	v_mul_f32_e32 v14, v14, v18
	v_mul_f32_e32 v15, v15, v19
	v_mul_f32_e32 v20, v20, v72
	v_mul_f32_e32 v21, v21, v73
	v_mul_f32_e32 v22, v22, v74
	v_mul_f32_e32 v23, v23, v75
	v_mul_f32_e32 v20, v20, v12
	v_mul_f32_e32 v21, v21, v13
	v_mul_f32_e32 v22, v22, v14
	v_mul_f32_e32 v23, v23, v15
	v_cvt_pk_bf16_f32 v20, v20, v21
	v_cvt_pk_bf16_f32 v21, v22, v23
	global_store_dwordx2 v204, v[20:21], s[30:31] offset:544
	s_waitcnt vmcnt(39)
	v_lshlrev_b32_e32 v12, 16, v28
	v_and_b32_e32 v13, 0xffff0000, v28
	v_lshlrev_b32_e32 v14, 16, v29
	v_and_b32_e32 v15, 0xffff0000, v29
	v_mul_f32_e32 v16, 0xbfb8aa3b, v12
	v_mul_f32_e32 v17, 0xbfb8aa3b, v13
	v_mul_f32_e32 v18, 0xbfb8aa3b, v14
	v_mul_f32_e32 v19, 0xbfb8aa3b, v15
	v_exp_f32_e32 v16, v16
	v_exp_f32_e32 v17, v17
	v_exp_f32_e32 v18, v18
	v_exp_f32_e32 v19, v19
	v_lshlrev_b32_e32 v20, 16, v104
	v_and_b32_e32 v21, 0xffff0000, v104
	v_lshlrev_b32_e32 v22, 16, v105
	v_and_b32_e32 v23, 0xffff0000, v105
	v_add_f32_e32 v16, 1.0, v16
	v_add_f32_e32 v17, 1.0, v17
	v_add_f32_e32 v18, 1.0, v18
	v_add_f32_e32 v19, 1.0, v19
	v_rcp_f32_e32 v16, v16
	v_rcp_f32_e32 v17, v17
	v_rcp_f32_e32 v18, v18
	v_rcp_f32_e32 v19, v19
	v_sub_f32_e32 v20, v20, v227
	v_sub_f32_e32 v21, v21, v227
	v_sub_f32_e32 v22, v22, v227
	v_sub_f32_e32 v23, v23, v227
	v_mul_f32_e32 v20, v20, v228
	v_mul_f32_e32 v21, v21, v228
	v_mul_f32_e32 v22, v22, v228
	v_mul_f32_e32 v23, v23, v228
	v_mul_f32_e32 v12, v12, v16
	v_mul_f32_e32 v13, v13, v17
	v_mul_f32_e32 v14, v14, v18
	v_mul_f32_e32 v15, v15, v19
	v_mul_f32_e32 v20, v20, v76
	v_mul_f32_e32 v21, v21, v77
	v_mul_f32_e32 v22, v22, v78
	v_mul_f32_e32 v23, v23, v79
	v_mul_f32_e32 v20, v20, v12
	v_mul_f32_e32 v21, v21, v13
	v_mul_f32_e32 v22, v22, v14
	v_mul_f32_e32 v23, v23, v15
	v_cvt_pk_bf16_f32 v20, v20, v21
	v_cvt_pk_bf16_f32 v21, v22, v23
	global_store_dwordx2 v204, v[20:21], s[30:31] offset:576
	s_waitcnt vmcnt(36)
	v_lshlrev_b32_e32 v12, 16, v30
	v_and_b32_e32 v13, 0xffff0000, v30
	v_lshlrev_b32_e32 v14, 16, v31
	v_and_b32_e32 v15, 0xffff0000, v31
	v_mul_f32_e32 v16, 0xbfb8aa3b, v12
	v_mul_f32_e32 v17, 0xbfb8aa3b, v13
	v_mul_f32_e32 v18, 0xbfb8aa3b, v14
	v_mul_f32_e32 v19, 0xbfb8aa3b, v15
	v_exp_f32_e32 v16, v16
	v_exp_f32_e32 v17, v17
	v_exp_f32_e32 v18, v18
	v_exp_f32_e32 v19, v19
	v_lshlrev_b32_e32 v20, 16, v106
	v_and_b32_e32 v21, 0xffff0000, v106
	v_lshlrev_b32_e32 v22, 16, v107
	v_and_b32_e32 v23, 0xffff0000, v107
	v_add_f32_e32 v16, 1.0, v16
	v_add_f32_e32 v17, 1.0, v17
	v_add_f32_e32 v18, 1.0, v18
	v_add_f32_e32 v19, 1.0, v19
	v_rcp_f32_e32 v16, v16
	v_rcp_f32_e32 v17, v17
	v_rcp_f32_e32 v18, v18
	v_rcp_f32_e32 v19, v19
	v_sub_f32_e32 v20, v20, v227
	v_sub_f32_e32 v21, v21, v227
	v_sub_f32_e32 v22, v22, v227
	v_sub_f32_e32 v23, v23, v227
	v_mul_f32_e32 v20, v20, v228
	v_mul_f32_e32 v21, v21, v228
	v_mul_f32_e32 v22, v22, v228
	v_mul_f32_e32 v23, v23, v228
	v_mul_f32_e32 v12, v12, v16
	v_mul_f32_e32 v13, v13, v17
	v_mul_f32_e32 v14, v14, v18
	v_mul_f32_e32 v15, v15, v19
	v_mul_f32_e32 v20, v20, v80
	v_mul_f32_e32 v21, v21, v81
	v_mul_f32_e32 v22, v22, v82
	v_mul_f32_e32 v23, v23, v83
	v_mul_f32_e32 v20, v20, v12
	v_mul_f32_e32 v21, v21, v13
	v_mul_f32_e32 v22, v22, v14
	v_mul_f32_e32 v23, v23, v15
	v_cvt_pk_bf16_f32 v20, v20, v21
	v_cvt_pk_bf16_f32 v21, v22, v23
	global_store_dwordx2 v204, v[20:21], s[30:31] offset:608
	s_waitcnt vmcnt(33)
	v_lshlrev_b32_e32 v12, 16, v32
	v_and_b32_e32 v13, 0xffff0000, v32
	v_lshlrev_b32_e32 v14, 16, v33
	v_and_b32_e32 v15, 0xffff0000, v33
	v_mul_f32_e32 v16, 0xbfb8aa3b, v12
	v_mul_f32_e32 v17, 0xbfb8aa3b, v13
	v_mul_f32_e32 v18, 0xbfb8aa3b, v14
	v_mul_f32_e32 v19, 0xbfb8aa3b, v15
	v_exp_f32_e32 v16, v16
	v_exp_f32_e32 v17, v17
	v_exp_f32_e32 v18, v18
	v_exp_f32_e32 v19, v19
	v_lshlrev_b32_e32 v20, 16, v108
	v_and_b32_e32 v21, 0xffff0000, v108
	v_lshlrev_b32_e32 v22, 16, v109
	v_and_b32_e32 v23, 0xffff0000, v109
	v_add_f32_e32 v16, 1.0, v16
	v_add_f32_e32 v17, 1.0, v17
	v_add_f32_e32 v18, 1.0, v18
	v_add_f32_e32 v19, 1.0, v19
	v_rcp_f32_e32 v16, v16
	v_rcp_f32_e32 v17, v17
	v_rcp_f32_e32 v18, v18
	v_rcp_f32_e32 v19, v19
	v_sub_f32_e32 v20, v20, v227
	v_sub_f32_e32 v21, v21, v227
	v_sub_f32_e32 v22, v22, v227
	v_sub_f32_e32 v23, v23, v227
	v_mul_f32_e32 v20, v20, v228
	v_mul_f32_e32 v21, v21, v228
	v_mul_f32_e32 v22, v22, v228
	v_mul_f32_e32 v23, v23, v228
	v_mul_f32_e32 v12, v12, v16
	v_mul_f32_e32 v13, v13, v17
	v_mul_f32_e32 v14, v14, v18
	v_mul_f32_e32 v15, v15, v19
	v_mul_f32_e32 v20, v20, v84
	v_mul_f32_e32 v21, v21, v85
	v_mul_f32_e32 v22, v22, v86
	v_mul_f32_e32 v23, v23, v87
	v_mul_f32_e32 v20, v20, v12
	v_mul_f32_e32 v21, v21, v13
	v_mul_f32_e32 v22, v22, v14
	v_mul_f32_e32 v23, v23, v15
	v_cvt_pk_bf16_f32 v20, v20, v21
	v_cvt_pk_bf16_f32 v21, v22, v23
	global_store_dwordx2 v204, v[20:21], s[30:31] offset:640
	s_waitcnt vmcnt(30)
	v_lshlrev_b32_e32 v12, 16, v34
	v_and_b32_e32 v13, 0xffff0000, v34
	v_lshlrev_b32_e32 v14, 16, v35
	v_and_b32_e32 v15, 0xffff0000, v35
	v_mul_f32_e32 v16, 0xbfb8aa3b, v12
	v_mul_f32_e32 v17, 0xbfb8aa3b, v13
	v_mul_f32_e32 v18, 0xbfb8aa3b, v14
	v_mul_f32_e32 v19, 0xbfb8aa3b, v15
	v_exp_f32_e32 v16, v16
	v_exp_f32_e32 v17, v17
	v_exp_f32_e32 v18, v18
	v_exp_f32_e32 v19, v19
	v_lshlrev_b32_e32 v20, 16, v110
	v_and_b32_e32 v21, 0xffff0000, v110
	v_lshlrev_b32_e32 v22, 16, v111
	v_and_b32_e32 v23, 0xffff0000, v111
	v_add_f32_e32 v16, 1.0, v16
	v_add_f32_e32 v17, 1.0, v17
	v_add_f32_e32 v18, 1.0, v18
	v_add_f32_e32 v19, 1.0, v19
	v_rcp_f32_e32 v16, v16
	v_rcp_f32_e32 v17, v17
	v_rcp_f32_e32 v18, v18
	v_rcp_f32_e32 v19, v19
	v_sub_f32_e32 v20, v20, v227
	v_sub_f32_e32 v21, v21, v227
	v_sub_f32_e32 v22, v22, v227
	v_sub_f32_e32 v23, v23, v227
	v_mul_f32_e32 v20, v20, v228
	v_mul_f32_e32 v21, v21, v228
	v_mul_f32_e32 v22, v22, v228
	v_mul_f32_e32 v23, v23, v228
	v_mul_f32_e32 v12, v12, v16
	v_mul_f32_e32 v13, v13, v17
	v_mul_f32_e32 v14, v14, v18
	v_mul_f32_e32 v15, v15, v19
	v_mul_f32_e32 v20, v20, v88
	v_mul_f32_e32 v21, v21, v89
	v_mul_f32_e32 v22, v22, v90
	v_mul_f32_e32 v23, v23, v91
	v_mul_f32_e32 v20, v20, v12
	v_mul_f32_e32 v21, v21, v13
	v_mul_f32_e32 v22, v22, v14
	v_mul_f32_e32 v23, v23, v15
	v_cvt_pk_bf16_f32 v20, v20, v21
	v_cvt_pk_bf16_f32 v21, v22, v23
	global_store_dwordx2 v204, v[20:21], s[30:31] offset:672
	s_waitcnt vmcnt(27)
	v_lshlrev_b32_e32 v12, 16, v36
	v_and_b32_e32 v13, 0xffff0000, v36
	v_lshlrev_b32_e32 v14, 16, v37
	v_and_b32_e32 v15, 0xffff0000, v37
	v_mul_f32_e32 v16, 0xbfb8aa3b, v12
	v_mul_f32_e32 v17, 0xbfb8aa3b, v13
	v_mul_f32_e32 v18, 0xbfb8aa3b, v14
	v_mul_f32_e32 v19, 0xbfb8aa3b, v15
	v_exp_f32_e32 v16, v16
	v_exp_f32_e32 v17, v17
	v_exp_f32_e32 v18, v18
	v_exp_f32_e32 v19, v19
	v_lshlrev_b32_e32 v20, 16, v112
	v_and_b32_e32 v21, 0xffff0000, v112
	v_lshlrev_b32_e32 v22, 16, v113
	v_and_b32_e32 v23, 0xffff0000, v113
	v_add_f32_e32 v16, 1.0, v16
	v_add_f32_e32 v17, 1.0, v17
	v_add_f32_e32 v18, 1.0, v18
	v_add_f32_e32 v19, 1.0, v19
	v_rcp_f32_e32 v16, v16
	v_rcp_f32_e32 v17, v17
	v_rcp_f32_e32 v18, v18
	v_rcp_f32_e32 v19, v19
	v_sub_f32_e32 v20, v20, v227
	v_sub_f32_e32 v21, v21, v227
	v_sub_f32_e32 v22, v22, v227
	v_sub_f32_e32 v23, v23, v227
	v_mul_f32_e32 v20, v20, v228
	v_mul_f32_e32 v21, v21, v228
	v_mul_f32_e32 v22, v22, v228
	v_mul_f32_e32 v23, v23, v228
	v_mul_f32_e32 v12, v12, v16
	v_mul_f32_e32 v13, v13, v17
	v_mul_f32_e32 v14, v14, v18
	v_mul_f32_e32 v15, v15, v19
	v_mul_f32_e32 v20, v20, v92
	v_mul_f32_e32 v21, v21, v93
	v_mul_f32_e32 v22, v22, v94
	v_mul_f32_e32 v23, v23, v95
	v_mul_f32_e32 v20, v20, v12
	v_mul_f32_e32 v21, v21, v13
	v_mul_f32_e32 v22, v22, v14
	v_mul_f32_e32 v23, v23, v15
	v_cvt_pk_bf16_f32 v20, v20, v21
	v_cvt_pk_bf16_f32 v21, v22, v23
	global_store_dwordx2 v204, v[20:21], s[30:31] offset:704
	s_waitcnt vmcnt(24)
	v_lshlrev_b32_e32 v12, 16, v38
	v_and_b32_e32 v13, 0xffff0000, v38
	v_lshlrev_b32_e32 v14, 16, v39
	v_and_b32_e32 v15, 0xffff0000, v39
	v_mul_f32_e32 v16, 0xbfb8aa3b, v12
	v_mul_f32_e32 v17, 0xbfb8aa3b, v13
	v_mul_f32_e32 v18, 0xbfb8aa3b, v14
	v_mul_f32_e32 v19, 0xbfb8aa3b, v15
	v_exp_f32_e32 v16, v16
	v_exp_f32_e32 v17, v17
	v_exp_f32_e32 v18, v18
	v_exp_f32_e32 v19, v19
	v_lshlrev_b32_e32 v20, 16, v114
	v_and_b32_e32 v21, 0xffff0000, v114
	v_lshlrev_b32_e32 v22, 16, v115
	v_and_b32_e32 v23, 0xffff0000, v115
	v_add_f32_e32 v16, 1.0, v16
	v_add_f32_e32 v17, 1.0, v17
	v_add_f32_e32 v18, 1.0, v18
	v_add_f32_e32 v19, 1.0, v19
	v_rcp_f32_e32 v16, v16
	v_rcp_f32_e32 v17, v17
	v_rcp_f32_e32 v18, v18
	v_rcp_f32_e32 v19, v19
	v_sub_f32_e32 v20, v20, v227
	v_sub_f32_e32 v21, v21, v227
	v_sub_f32_e32 v22, v22, v227
	v_sub_f32_e32 v23, v23, v227
	v_mul_f32_e32 v20, v20, v228
	v_mul_f32_e32 v21, v21, v228
	v_mul_f32_e32 v22, v22, v228
	v_mul_f32_e32 v23, v23, v228
	v_mul_f32_e32 v12, v12, v16
	v_mul_f32_e32 v13, v13, v17
	v_mul_f32_e32 v14, v14, v18
	v_mul_f32_e32 v15, v15, v19
	v_mul_f32_e32 v20, v20, v96
	v_mul_f32_e32 v21, v21, v97
	v_mul_f32_e32 v22, v22, v98
	v_mul_f32_e32 v23, v23, v99
	v_mul_f32_e32 v20, v20, v12
	v_mul_f32_e32 v21, v21, v13
	v_mul_f32_e32 v22, v22, v14
	v_mul_f32_e32 v23, v23, v15
	v_cvt_pk_bf16_f32 v20, v20, v21
	v_cvt_pk_bf16_f32 v21, v22, v23
	global_store_dwordx2 v204, v[20:21], s[30:31] offset:736
	s_waitcnt vmcnt(21)
	v_lshlrev_b32_e32 v12, 16, v40
	v_and_b32_e32 v13, 0xffff0000, v40
	v_lshlrev_b32_e32 v14, 16, v41
	v_and_b32_e32 v15, 0xffff0000, v41
	v_mul_f32_e32 v16, 0xbfb8aa3b, v12
	v_mul_f32_e32 v17, 0xbfb8aa3b, v13
	v_mul_f32_e32 v18, 0xbfb8aa3b, v14
	v_mul_f32_e32 v19, 0xbfb8aa3b, v15
	v_exp_f32_e32 v16, v16
	v_exp_f32_e32 v17, v17
	v_exp_f32_e32 v18, v18
	v_exp_f32_e32 v19, v19
	v_lshlrev_b32_e32 v20, 16, v116
	v_and_b32_e32 v21, 0xffff0000, v116
	v_lshlrev_b32_e32 v22, 16, v117
	v_and_b32_e32 v23, 0xffff0000, v117
	v_add_f32_e32 v16, 1.0, v16
	v_add_f32_e32 v17, 1.0, v17
	v_add_f32_e32 v18, 1.0, v18
	v_add_f32_e32 v19, 1.0, v19
	v_rcp_f32_e32 v16, v16
	v_rcp_f32_e32 v17, v17
	v_rcp_f32_e32 v18, v18
	v_rcp_f32_e32 v19, v19
	v_sub_f32_e32 v20, v20, v227
	v_sub_f32_e32 v21, v21, v227
	v_sub_f32_e32 v22, v22, v227
	v_sub_f32_e32 v23, v23, v227
	v_mul_f32_e32 v20, v20, v228
	v_mul_f32_e32 v21, v21, v228
	v_mul_f32_e32 v22, v22, v228
	v_mul_f32_e32 v23, v23, v228
	v_mul_f32_e32 v12, v12, v16
	v_mul_f32_e32 v13, v13, v17
	v_mul_f32_e32 v14, v14, v18
	v_mul_f32_e32 v15, v15, v19
	v_mul_f32_e32 v20, v20, v132
	v_mul_f32_e32 v21, v21, v133
	v_mul_f32_e32 v22, v22, v134
	v_mul_f32_e32 v23, v23, v135
	v_mul_f32_e32 v20, v20, v12
	v_mul_f32_e32 v21, v21, v13
	v_mul_f32_e32 v22, v22, v14
	v_mul_f32_e32 v23, v23, v15
	v_cvt_pk_bf16_f32 v20, v20, v21
	v_cvt_pk_bf16_f32 v21, v22, v23
	global_store_dwordx2 v204, v[20:21], s[30:31] offset:768
	s_waitcnt vmcnt(18)
	v_lshlrev_b32_e32 v12, 16, v42
	v_and_b32_e32 v13, 0xffff0000, v42
	v_lshlrev_b32_e32 v14, 16, v43
	v_and_b32_e32 v15, 0xffff0000, v43
	v_mul_f32_e32 v16, 0xbfb8aa3b, v12
	v_mul_f32_e32 v17, 0xbfb8aa3b, v13
	v_mul_f32_e32 v18, 0xbfb8aa3b, v14
	v_mul_f32_e32 v19, 0xbfb8aa3b, v15
	v_exp_f32_e32 v16, v16
	v_exp_f32_e32 v17, v17
	v_exp_f32_e32 v18, v18
	v_exp_f32_e32 v19, v19
	v_lshlrev_b32_e32 v20, 16, v118
	v_and_b32_e32 v21, 0xffff0000, v118
	v_lshlrev_b32_e32 v22, 16, v119
	v_and_b32_e32 v23, 0xffff0000, v119
	v_add_f32_e32 v16, 1.0, v16
	v_add_f32_e32 v17, 1.0, v17
	v_add_f32_e32 v18, 1.0, v18
	v_add_f32_e32 v19, 1.0, v19
	v_rcp_f32_e32 v16, v16
	v_rcp_f32_e32 v17, v17
	v_rcp_f32_e32 v18, v18
	v_rcp_f32_e32 v19, v19
	v_sub_f32_e32 v20, v20, v227
	v_sub_f32_e32 v21, v21, v227
	v_sub_f32_e32 v22, v22, v227
	v_sub_f32_e32 v23, v23, v227
	v_mul_f32_e32 v20, v20, v228
	v_mul_f32_e32 v21, v21, v228
	v_mul_f32_e32 v22, v22, v228
	v_mul_f32_e32 v23, v23, v228
	v_mul_f32_e32 v12, v12, v16
	v_mul_f32_e32 v13, v13, v17
	v_mul_f32_e32 v14, v14, v18
	v_mul_f32_e32 v15, v15, v19
	v_mul_f32_e32 v20, v20, v136
	v_mul_f32_e32 v21, v21, v137
	v_mul_f32_e32 v22, v22, v138
	v_mul_f32_e32 v23, v23, v139
	v_mul_f32_e32 v20, v20, v12
	v_mul_f32_e32 v21, v21, v13
	v_mul_f32_e32 v22, v22, v14
	v_mul_f32_e32 v23, v23, v15
	v_cvt_pk_bf16_f32 v20, v20, v21
	v_cvt_pk_bf16_f32 v21, v22, v23
	global_store_dwordx2 v204, v[20:21], s[30:31] offset:800
	s_waitcnt vmcnt(15)
	v_lshlrev_b32_e32 v12, 16, v44
	v_and_b32_e32 v13, 0xffff0000, v44
	v_lshlrev_b32_e32 v14, 16, v45
	v_and_b32_e32 v15, 0xffff0000, v45
	v_mul_f32_e32 v16, 0xbfb8aa3b, v12
	v_mul_f32_e32 v17, 0xbfb8aa3b, v13
	v_mul_f32_e32 v18, 0xbfb8aa3b, v14
	v_mul_f32_e32 v19, 0xbfb8aa3b, v15
	v_exp_f32_e32 v16, v16
	v_exp_f32_e32 v17, v17
	v_exp_f32_e32 v18, v18
	v_exp_f32_e32 v19, v19
	v_lshlrev_b32_e32 v20, 16, v120
	v_and_b32_e32 v21, 0xffff0000, v120
	v_lshlrev_b32_e32 v22, 16, v121
	v_and_b32_e32 v23, 0xffff0000, v121
	v_add_f32_e32 v16, 1.0, v16
	v_add_f32_e32 v17, 1.0, v17
	v_add_f32_e32 v18, 1.0, v18
	v_add_f32_e32 v19, 1.0, v19
	v_rcp_f32_e32 v16, v16
	v_rcp_f32_e32 v17, v17
	v_rcp_f32_e32 v18, v18
	v_rcp_f32_e32 v19, v19
	v_sub_f32_e32 v20, v20, v227
	v_sub_f32_e32 v21, v21, v227
	v_sub_f32_e32 v22, v22, v227
	v_sub_f32_e32 v23, v23, v227
	v_mul_f32_e32 v20, v20, v228
	v_mul_f32_e32 v21, v21, v228
	v_mul_f32_e32 v22, v22, v228
	v_mul_f32_e32 v23, v23, v228
	v_mul_f32_e32 v12, v12, v16
	v_mul_f32_e32 v13, v13, v17
	v_mul_f32_e32 v14, v14, v18
	v_mul_f32_e32 v15, v15, v19
	v_mul_f32_e32 v20, v20, v144
	v_mul_f32_e32 v21, v21, v145
	v_mul_f32_e32 v22, v22, v146
	v_mul_f32_e32 v23, v23, v147
	v_mul_f32_e32 v20, v20, v12
	v_mul_f32_e32 v21, v21, v13
	v_mul_f32_e32 v22, v22, v14
	v_mul_f32_e32 v23, v23, v15
	v_cvt_pk_bf16_f32 v20, v20, v21
	v_cvt_pk_bf16_f32 v21, v22, v23
	global_store_dwordx2 v204, v[20:21], s[30:31] offset:832
	s_waitcnt vmcnt(12)
	v_lshlrev_b32_e32 v12, 16, v46
	v_and_b32_e32 v13, 0xffff0000, v46
	v_lshlrev_b32_e32 v14, 16, v47
	v_and_b32_e32 v15, 0xffff0000, v47
	v_mul_f32_e32 v16, 0xbfb8aa3b, v12
	v_mul_f32_e32 v17, 0xbfb8aa3b, v13
	v_mul_f32_e32 v18, 0xbfb8aa3b, v14
	v_mul_f32_e32 v19, 0xbfb8aa3b, v15
	v_exp_f32_e32 v16, v16
	v_exp_f32_e32 v17, v17
	v_exp_f32_e32 v18, v18
	v_exp_f32_e32 v19, v19
	v_lshlrev_b32_e32 v20, 16, v122
	v_and_b32_e32 v21, 0xffff0000, v122
	v_lshlrev_b32_e32 v22, 16, v123
	v_and_b32_e32 v23, 0xffff0000, v123
	v_add_f32_e32 v16, 1.0, v16
	v_add_f32_e32 v17, 1.0, v17
	v_add_f32_e32 v18, 1.0, v18
	v_add_f32_e32 v19, 1.0, v19
	v_rcp_f32_e32 v16, v16
	v_rcp_f32_e32 v17, v17
	v_rcp_f32_e32 v18, v18
	v_rcp_f32_e32 v19, v19
	v_sub_f32_e32 v20, v20, v227
	v_sub_f32_e32 v21, v21, v227
	v_sub_f32_e32 v22, v22, v227
	v_sub_f32_e32 v23, v23, v227
	v_mul_f32_e32 v20, v20, v228
	v_mul_f32_e32 v21, v21, v228
	v_mul_f32_e32 v22, v22, v228
	v_mul_f32_e32 v23, v23, v228
	v_mul_f32_e32 v12, v12, v16
	v_mul_f32_e32 v13, v13, v17
	v_mul_f32_e32 v14, v14, v18
	v_mul_f32_e32 v15, v15, v19
	v_mul_f32_e32 v20, v20, v148
	v_mul_f32_e32 v21, v21, v149
	v_mul_f32_e32 v22, v22, v150
	v_mul_f32_e32 v23, v23, v151
	v_mul_f32_e32 v20, v20, v12
	v_mul_f32_e32 v21, v21, v13
	v_mul_f32_e32 v22, v22, v14
	v_mul_f32_e32 v23, v23, v15
	v_cvt_pk_bf16_f32 v20, v20, v21
	v_cvt_pk_bf16_f32 v21, v22, v23
	global_store_dwordx2 v204, v[20:21], s[30:31] offset:864
	s_waitcnt vmcnt(9)
	v_lshlrev_b32_e32 v12, 16, v48
	v_and_b32_e32 v13, 0xffff0000, v48
	v_lshlrev_b32_e32 v14, 16, v49
	v_and_b32_e32 v15, 0xffff0000, v49
	v_mul_f32_e32 v16, 0xbfb8aa3b, v12
	v_mul_f32_e32 v17, 0xbfb8aa3b, v13
	v_mul_f32_e32 v18, 0xbfb8aa3b, v14
	v_mul_f32_e32 v19, 0xbfb8aa3b, v15
	v_exp_f32_e32 v16, v16
	v_exp_f32_e32 v17, v17
	v_exp_f32_e32 v18, v18
	v_exp_f32_e32 v19, v19
	v_lshlrev_b32_e32 v20, 16, v124
	v_and_b32_e32 v21, 0xffff0000, v124
	v_lshlrev_b32_e32 v22, 16, v125
	v_and_b32_e32 v23, 0xffff0000, v125
	v_add_f32_e32 v16, 1.0, v16
	v_add_f32_e32 v17, 1.0, v17
	v_add_f32_e32 v18, 1.0, v18
	v_add_f32_e32 v19, 1.0, v19
	v_rcp_f32_e32 v16, v16
	v_rcp_f32_e32 v17, v17
	v_rcp_f32_e32 v18, v18
	v_rcp_f32_e32 v19, v19
	v_sub_f32_e32 v20, v20, v227
	v_sub_f32_e32 v21, v21, v227
	v_sub_f32_e32 v22, v22, v227
	v_sub_f32_e32 v23, v23, v227
	v_mul_f32_e32 v20, v20, v228
	v_mul_f32_e32 v21, v21, v228
	v_mul_f32_e32 v22, v22, v228
	v_mul_f32_e32 v23, v23, v228
	v_mul_f32_e32 v12, v12, v16
	v_mul_f32_e32 v13, v13, v17
	v_mul_f32_e32 v14, v14, v18
	v_mul_f32_e32 v15, v15, v19
	v_mul_f32_e32 v20, v20, v152
	v_mul_f32_e32 v21, v21, v153
	v_mul_f32_e32 v22, v22, v154
	v_mul_f32_e32 v23, v23, v155
	v_mul_f32_e32 v20, v20, v12
	v_mul_f32_e32 v21, v21, v13
	v_mul_f32_e32 v22, v22, v14
	v_mul_f32_e32 v23, v23, v15
	v_cvt_pk_bf16_f32 v20, v20, v21
	v_cvt_pk_bf16_f32 v21, v22, v23
	global_store_dwordx2 v204, v[20:21], s[30:31] offset:896
	s_waitcnt vmcnt(6)
	v_lshlrev_b32_e32 v12, 16, v50
	v_and_b32_e32 v13, 0xffff0000, v50
	v_lshlrev_b32_e32 v14, 16, v51
	v_and_b32_e32 v15, 0xffff0000, v51
	v_mul_f32_e32 v16, 0xbfb8aa3b, v12
	v_mul_f32_e32 v17, 0xbfb8aa3b, v13
	v_mul_f32_e32 v18, 0xbfb8aa3b, v14
	v_mul_f32_e32 v19, 0xbfb8aa3b, v15
	v_exp_f32_e32 v16, v16
	v_exp_f32_e32 v17, v17
	v_exp_f32_e32 v18, v18
	v_exp_f32_e32 v19, v19
	v_lshlrev_b32_e32 v20, 16, v126
	v_and_b32_e32 v21, 0xffff0000, v126
	v_lshlrev_b32_e32 v22, 16, v127
	v_and_b32_e32 v23, 0xffff0000, v127
	v_add_f32_e32 v16, 1.0, v16
	v_add_f32_e32 v17, 1.0, v17
	v_add_f32_e32 v18, 1.0, v18
	v_add_f32_e32 v19, 1.0, v19
	v_rcp_f32_e32 v16, v16
	v_rcp_f32_e32 v17, v17
	v_rcp_f32_e32 v18, v18
	v_rcp_f32_e32 v19, v19
	v_sub_f32_e32 v20, v20, v227
	v_sub_f32_e32 v21, v21, v227
	v_sub_f32_e32 v22, v22, v227
	v_sub_f32_e32 v23, v23, v227
	v_mul_f32_e32 v20, v20, v228
	v_mul_f32_e32 v21, v21, v228
	v_mul_f32_e32 v22, v22, v228
	v_mul_f32_e32 v23, v23, v228
	v_mul_f32_e32 v12, v12, v16
	v_mul_f32_e32 v13, v13, v17
	v_mul_f32_e32 v14, v14, v18
	v_mul_f32_e32 v15, v15, v19
	v_mul_f32_e32 v20, v20, v156
	v_mul_f32_e32 v21, v21, v157
	v_mul_f32_e32 v22, v22, v158
	v_mul_f32_e32 v23, v23, v159
	v_mul_f32_e32 v20, v20, v12
	v_mul_f32_e32 v21, v21, v13
	v_mul_f32_e32 v22, v22, v14
	v_mul_f32_e32 v23, v23, v15
	v_cvt_pk_bf16_f32 v20, v20, v21
	v_cvt_pk_bf16_f32 v21, v22, v23
	global_store_dwordx2 v204, v[20:21], s[30:31] offset:928
	s_waitcnt vmcnt(3)
	v_lshlrev_b32_e32 v12, 16, v52
	v_and_b32_e32 v13, 0xffff0000, v52
	v_lshlrev_b32_e32 v14, 16, v53
	v_and_b32_e32 v15, 0xffff0000, v53
	v_mul_f32_e32 v16, 0xbfb8aa3b, v12
	v_mul_f32_e32 v17, 0xbfb8aa3b, v13
	v_mul_f32_e32 v18, 0xbfb8aa3b, v14
	v_mul_f32_e32 v19, 0xbfb8aa3b, v15
	v_exp_f32_e32 v16, v16
	v_exp_f32_e32 v17, v17
	v_exp_f32_e32 v18, v18
	v_exp_f32_e32 v19, v19
	v_lshlrev_b32_e32 v20, 16, v128
	v_and_b32_e32 v21, 0xffff0000, v128
	v_lshlrev_b32_e32 v22, 16, v129
	v_and_b32_e32 v23, 0xffff0000, v129
	v_add_f32_e32 v16, 1.0, v16
	v_add_f32_e32 v17, 1.0, v17
	v_add_f32_e32 v18, 1.0, v18
	v_add_f32_e32 v19, 1.0, v19
	v_rcp_f32_e32 v16, v16
	v_rcp_f32_e32 v17, v17
	v_rcp_f32_e32 v18, v18
	v_rcp_f32_e32 v19, v19
	v_sub_f32_e32 v20, v20, v227
	v_sub_f32_e32 v21, v21, v227
	v_sub_f32_e32 v22, v22, v227
	v_sub_f32_e32 v23, v23, v227
	v_mul_f32_e32 v20, v20, v228
	v_mul_f32_e32 v21, v21, v228
	v_mul_f32_e32 v22, v22, v228
	v_mul_f32_e32 v23, v23, v228
	v_mul_f32_e32 v12, v12, v16
	v_mul_f32_e32 v13, v13, v17
	v_mul_f32_e32 v14, v14, v18
	v_mul_f32_e32 v15, v15, v19
	v_mul_f32_e32 v20, v20, v160
	v_mul_f32_e32 v21, v21, v161
	v_mul_f32_e32 v22, v22, v162
	v_mul_f32_e32 v23, v23, v163
	v_mul_f32_e32 v20, v20, v12
	v_mul_f32_e32 v21, v21, v13
	v_mul_f32_e32 v22, v22, v14
	v_mul_f32_e32 v23, v23, v15
	v_cvt_pk_bf16_f32 v20, v20, v21
	v_cvt_pk_bf16_f32 v21, v22, v23
	global_store_dwordx2 v204, v[20:21], s[30:31] offset:960
	s_waitcnt vmcnt(0)
	v_lshlrev_b32_e32 v12, 16, v54
	v_and_b32_e32 v13, 0xffff0000, v54
	v_lshlrev_b32_e32 v14, 16, v55
	v_and_b32_e32 v15, 0xffff0000, v55
	v_mul_f32_e32 v16, 0xbfb8aa3b, v12
	v_mul_f32_e32 v17, 0xbfb8aa3b, v13
	v_mul_f32_e32 v18, 0xbfb8aa3b, v14
	v_mul_f32_e32 v19, 0xbfb8aa3b, v15
	v_exp_f32_e32 v16, v16
	v_exp_f32_e32 v17, v17
	v_exp_f32_e32 v18, v18
	v_exp_f32_e32 v19, v19
	v_lshlrev_b32_e32 v20, 16, v130
	v_and_b32_e32 v21, 0xffff0000, v130
	v_lshlrev_b32_e32 v22, 16, v131
	v_and_b32_e32 v23, 0xffff0000, v131
	v_add_f32_e32 v16, 1.0, v16
	v_add_f32_e32 v17, 1.0, v17
	v_add_f32_e32 v18, 1.0, v18
	v_add_f32_e32 v19, 1.0, v19
	v_rcp_f32_e32 v16, v16
	v_rcp_f32_e32 v17, v17
	v_rcp_f32_e32 v18, v18
	v_rcp_f32_e32 v19, v19
	v_sub_f32_e32 v20, v20, v227
	v_sub_f32_e32 v21, v21, v227
	v_sub_f32_e32 v22, v22, v227
	v_sub_f32_e32 v23, v23, v227
	v_mul_f32_e32 v20, v20, v228
	v_mul_f32_e32 v21, v21, v228
	v_mul_f32_e32 v22, v22, v228
	v_mul_f32_e32 v23, v23, v228
	v_mul_f32_e32 v12, v12, v16
	v_mul_f32_e32 v13, v13, v17
	v_mul_f32_e32 v14, v14, v18
	v_mul_f32_e32 v15, v15, v19
	v_mul_f32_e32 v20, v20, v164
	v_mul_f32_e32 v21, v21, v165
	v_mul_f32_e32 v22, v22, v166
	v_mul_f32_e32 v23, v23, v167
	v_mul_f32_e32 v20, v20, v12
	v_mul_f32_e32 v21, v21, v13
	v_mul_f32_e32 v22, v22, v14
	v_mul_f32_e32 v23, v23, v15
	v_cvt_pk_bf16_f32 v20, v20, v21
	v_cvt_pk_bf16_f32 v21, v22, v23
	global_store_dwordx2 v204, v[20:21], s[30:31] offset:992
	s_waitcnt vmcnt(0)
	s_add_i32 s6, s6, 1
	s_cmp_lt_i32 s6, 2
	s_cbranch_scc1 .Lintra_unit
	s_branch .LBB0_748

.Lsel_epilogue:
	s_waitcnt vmcnt(2)
	s_nop 7
	ds_bpermute_b32 v66, v180, v197
	s_waitcnt lgkmcnt(0)
	v_add_f32_e32 v197, v197, v66
	ds_bpermute_b32 v66, v181, v197
	v_lshlrev_b32_e32 v67, 16, v64
	v_mul_f32_e32 v67, 0xbfb8aa3b, v67
	v_exp_f32_e32 v67, v67
	s_waitcnt lgkmcnt(0)
	v_add_f32_e32 v197, v197, v66
	v_add_f32_e32 v67, 1.0, v67
	v_mul_f32_e32 v67, v67, v197
	v_rcp_f32_e32 v67, v67
	s_nop 0
	v_lshlrev_b32_e32 v144, 16, v24
	v_and_b32_e32 v145, 0xffff0000, v24
	v_lshlrev_b32_e32 v143, 16, v25
	v_and_b32_e32 v177, 0xffff0000, v25
	v_fmac_f32_e32 v144, v0, v67
	v_fmac_f32_e32 v145, v1, v67
	v_fmac_f32_e32 v143, v2, v67
	v_fmac_f32_e32 v177, v3, v67
	v_cvt_pk_bf16_f32 v24, v144, v145
	v_cvt_pk_bf16_f32 v25, v143, v177
	v_lshlrev_b32_e32 v144, 16, v26
	v_and_b32_e32 v145, 0xffff0000, v26
	v_lshlrev_b32_e32 v143, 16, v27
	v_and_b32_e32 v177, 0xffff0000, v27
	v_fmac_f32_e32 v144, v4, v67
	v_fmac_f32_e32 v145, v5, v67
	v_fmac_f32_e32 v143, v6, v67
	v_fmac_f32_e32 v177, v7, v67
	v_cvt_pk_bf16_f32 v26, v144, v145
	v_cvt_pk_bf16_f32 v27, v143, v177
	v_lshlrev_b32_e32 v144, 16, v28
	v_and_b32_e32 v145, 0xffff0000, v28
	v_lshlrev_b32_e32 v143, 16, v29
	v_and_b32_e32 v177, 0xffff0000, v29
	v_fmac_f32_e32 v144, v8, v67
	v_fmac_f32_e32 v145, v9, v67
	v_fmac_f32_e32 v143, v10, v67
	v_fmac_f32_e32 v177, v11, v67
	v_cvt_pk_bf16_f32 v28, v144, v145
	v_cvt_pk_bf16_f32 v29, v143, v177
	v_lshlrev_b32_e32 v144, 16, v30
	v_and_b32_e32 v145, 0xffff0000, v30
	v_lshlrev_b32_e32 v143, 16, v31
	v_and_b32_e32 v177, 0xffff0000, v31
	v_fmac_f32_e32 v144, v12, v67
	v_fmac_f32_e32 v145, v13, v67
	v_fmac_f32_e32 v143, v14, v67
	v_fmac_f32_e32 v177, v15, v67
	v_cvt_pk_bf16_f32 v30, v144, v145
	v_cvt_pk_bf16_f32 v31, v143, v177
	v_lshlrev_b32_e32 v66, 7, v202
	v_lshl_add_u32 v66, v182, 1, v66
	s_and_saveexec_b64 s[0:1], s[8:9]
	global_store_dwordx2 v66, v[24:25], s[40:41] offset:0
	global_store_dwordx2 v66, v[26:27], s[40:41] offset:32
	global_store_dwordx2 v66, v[28:29], s[40:41] offset:64
	global_store_dwordx2 v66, v[30:31], s[40:41] offset:96
	s_mov_b64 exec, s[0:1]
	s_add_i32 s60, s60, 1
	s_cmp_ge_i32 s60, 16
	s_cbranch_scc1 .Lsel_exit
	s_mov_b32 s26, s56
	s_lshr_b32 s61, s26, 6
	s_and_b32 s0, s60, 7
	s_cmp_lg_u32 s0, 0
	s_cbranch_scc1 .Lsel_samerun
	v_readfirstlane_b32 s1, v220
	s_waitcnt lgkmcnt(0)
	s_barrier
	s_and_b32 s0, s1, 3
	s_lshl_b32 s0, s0, 12
	s_cmp_lt_u32 s1, 4
	s_cselect_b32 s40, s18, s16
	s_cselect_b32 s41, s19, s17
	s_cselect_b32 s2, 1, 2
	s_lshl_b32 s2, s2, 14
	s_add_i32 s2, s2, s0
	s_add_i32 s62, s61, -1
	s_lshl_b32 s62, s62, 13
	s_add_i32 s0, s0, s62
	s_ashr_i32 s62, s0, 31
	s_add_u32 s40, s40, s0
	s_addc_u32 s41, s41, s62
	s_add_i32 m0, s2, 0
	s_nop 0
	global_load_lds_dwordx4 v140, s[40:41]
	s_add_i32 m0, s2, 1024
	s_add_u32 s40, s40, 0x400
	s_addc_u32 s41, s41, 0
	global_load_lds_dwordx4 v140, s[40:41]
	s_add_i32 m0, s2, 2048
	s_add_u32 s40, s40, 0x400
	s_addc_u32 s41, s41, 0
	global_load_lds_dwordx4 v140, s[40:41]
	s_add_i32 m0, s2, 3072
	s_add_u32 s40, s40, 0x400
	s_addc_u32 s41, s41, 0
	global_load_lds_dwordx4 v140, s[40:41]
	s_waitcnt vmcnt(0)
	s_barrier
.Lsel_samerun:
	s_lshr_b32 s0, s26, 6
	s_add_i32 s0, s0, 1
	s_min_i32 s28, s0, 16
	s_mov_b32 s29, 0
	s_mov_b32 s30, 0
	v_mov_b32_e32 v196, 0xf149f2ca
	v_mov_b32_e32 v197, 0
	v_mov_b32_e32 v0, 0
	v_mov_b32_e32 v1, 0
	v_mov_b32_e32 v2, 0
	v_mov_b32_e32 v3, 0
	v_mov_b32_e32 v4, 0
	v_mov_b32_e32 v5, 0
	v_mov_b32_e32 v6, 0
	v_mov_b32_e32 v7, 0
	v_mov_b32_e32 v8, 0
	v_mov_b32_e32 v9, 0
	v_mov_b32_e32 v10, 0
	v_mov_b32_e32 v11, 0
	v_mov_b32_e32 v12, 0
	v_mov_b32_e32 v13, 0
	v_mov_b32_e32 v14, 0
	v_mov_b32_e32 v15, 0
	s_cmp_eq_u32 s51, 0
	s_cbranch_scc1 .Lsel_stepB
	s_branch .Lsel_stepA

.LBB0_1015:
	v_lshl_add_u32 v150, s51, 8, v143
	v_lshl_or_b32 v148, s52, 8, v153
	v_ashrrev_i32_e32 v151, 31, v150
	v_ashrrev_i32_e32 v149, 31, v148
	v_lshlrev_b64 v[140:141], 10, v[150:151]
	v_lshl_add_u64 v[140:141], v[140:141], 0, v[148:149]
	v_lshl_add_u64 v[140:141], v[140:141], 2, s[18:19]
	s_mov_b64 s[0:1], 0x10000
	v_lshl_add_u64 v[236:237], v[140:141], 0, s[0:1]
	s_mov_b64 s[0:1], 0x20000
	v_lshl_add_u64 v[238:239], v[140:141], 0, s[0:1]
	s_mov_b64 s[0:1], 0x30000
	v_lshl_add_u64 v[240:241], v[140:141], 0, s[0:1]
	s_mov_b64 s[0:1], 0x80000
	v_lshl_add_u64 v[242:243], v[140:141], 0, s[0:1]
	s_mov_b64 s[0:1], 0x90000
	v_lshl_add_u64 v[244:245], v[140:141], 0, s[0:1]
	s_mov_b64 s[0:1], 0xa0000
	v_lshl_add_u64 v[246:247], v[140:141], 0, s[0:1]
	s_mov_b64 s[0:1], 0xb0000
	v_lshl_add_u64 v[248:249], v[140:141], 0, s[0:1]
	global_load_dwordx4 v[156:159], v[140:141], off offset:0
	global_load_dwordx4 v[160:163], v[140:141], off offset:16
	global_load_dwordx4 v[164:167], v[140:141], off offset:512
	global_load_dwordx4 v[168:171], v[140:141], off offset:528
	global_load_dwordx4 v[172:175], v[236:237], off offset:0
	global_load_dwordx4 v[176:179], v[236:237], off offset:16
	global_load_dwordx4 v[180:183], v[236:237], off offset:512
	global_load_dwordx4 v[184:187], v[236:237], off offset:528
	global_load_dwordx4 v[188:191], v[238:239], off offset:0
	global_load_dwordx4 v[192:195], v[238:239], off offset:16
	global_load_dwordx4 v[196:199], v[238:239], off offset:512
	global_load_dwordx4 v[200:203], v[238:239], off offset:528
	global_load_dwordx4 v[204:207], v[240:241], off offset:0
	global_load_dwordx4 v[220:223], v[240:241], off offset:16
	global_load_dwordx4 v[224:227], v[240:241], off offset:512
	global_load_dwordx4 v[228:231], v[240:241], off offset:528
	s_waitcnt vmcnt(15)
	v_pk_add_f32 v[128:129], v[128:129], v[158:159]
	v_pk_add_f32 v[126:127], v[126:127], v[156:157]
	global_load_dwordx4 v[156:159], v[242:243], off offset:0
	s_waitcnt vmcnt(15)
	v_pk_add_f32 v[124:125], v[124:125], v[162:163]
	v_pk_add_f32 v[122:123], v[122:123], v[160:161]
	global_load_dwordx4 v[160:163], v[242:243], off offset:16
	s_waitcnt vmcnt(15)
	v_pk_add_f32 v[120:121], v[120:121], v[166:167]
	v_pk_add_f32 v[118:119], v[118:119], v[164:165]
	global_load_dwordx4 v[164:167], v[242:243], off offset:512
	s_waitcnt vmcnt(15)
	v_pk_add_f32 v[116:117], v[116:117], v[170:171]
	v_pk_add_f32 v[114:115], v[114:115], v[168:169]
	global_load_dwordx4 v[168:171], v[242:243], off offset:528
	s_waitcnt vmcnt(15)
	v_pk_add_f32 v[112:113], v[112:113], v[174:175]
	v_pk_add_f32 v[110:111], v[110:111], v[172:173]
	global_load_dwordx4 v[172:175], v[244:245], off offset:0
	s_waitcnt vmcnt(15)
	v_pk_add_f32 v[108:109], v[108:109], v[178:179]
	v_pk_add_f32 v[106:107], v[106:107], v[176:177]
	global_load_dwordx4 v[176:179], v[244:245], off offset:16
	s_waitcnt vmcnt(15)
	v_pk_add_f32 v[104:105], v[104:105], v[182:183]
	v_pk_add_f32 v[102:103], v[102:103], v[180:181]
	global_load_dwordx4 v[180:183], v[244:245], off offset:512
	s_waitcnt vmcnt(15)
	v_pk_add_f32 v[100:101], v[100:101], v[186:187]
	v_pk_add_f32 v[98:99], v[98:99], v[184:185]
	global_load_dwordx4 v[184:187], v[244:245], off offset:528
	s_waitcnt vmcnt(15)
	v_pk_add_f32 v[96:97], v[96:97], v[190:191]
	v_pk_add_f32 v[94:95], v[94:95], v[188:189]
	global_load_dwordx4 v[188:191], v[246:247], off offset:0
	s_waitcnt vmcnt(15)
	v_pk_add_f32 v[92:93], v[92:93], v[194:195]
	v_pk_add_f32 v[90:91], v[90:91], v[192:193]
	global_load_dwordx4 v[192:195], v[246:247], off offset:16
	s_waitcnt vmcnt(15)
	v_pk_add_f32 v[88:89], v[88:89], v[198:199]
	v_pk_add_f32 v[86:87], v[86:87], v[196:197]
	global_load_dwordx4 v[196:199], v[246:247], off offset:512
	s_waitcnt vmcnt(15)
	v_pk_add_f32 v[84:85], v[84:85], v[202:203]
	v_pk_add_f32 v[82:83], v[82:83], v[200:201]
	global_load_dwordx4 v[200:203], v[246:247], off offset:528
	s_waitcnt vmcnt(15)
	v_pk_add_f32 v[80:81], v[80:81], v[206:207]
	v_pk_add_f32 v[78:79], v[78:79], v[204:205]
	global_load_dwordx4 v[204:207], v[248:249], off offset:0
	s_waitcnt vmcnt(15)
	v_pk_add_f32 v[76:77], v[76:77], v[222:223]
	v_pk_add_f32 v[74:75], v[74:75], v[220:221]
	global_load_dwordx4 v[220:223], v[248:249], off offset:16
	s_waitcnt vmcnt(15)
	v_pk_add_f32 v[72:73], v[72:73], v[226:227]
	v_pk_add_f32 v[70:71], v[70:71], v[224:225]
	global_load_dwordx4 v[224:227], v[248:249], off offset:512
	s_waitcnt vmcnt(15)
	v_pk_add_f32 v[68:69], v[68:69], v[230:231]
	v_pk_add_f32 v[66:67], v[66:67], v[228:229]
	global_load_dwordx4 v[228:231], v[248:249], off offset:528
	s_waitcnt vmcnt(15)
	v_pk_add_f32 v[62:63], v[62:63], v[158:159]
	v_pk_add_f32 v[60:61], v[60:61], v[156:157]
	s_waitcnt vmcnt(14)
	v_pk_add_f32 v[58:59], v[58:59], v[162:163]
	v_pk_add_f32 v[56:57], v[56:57], v[160:161]
	s_waitcnt vmcnt(13)
	v_pk_add_f32 v[54:55], v[54:55], v[166:167]
	v_pk_add_f32 v[52:53], v[52:53], v[164:165]
	s_waitcnt vmcnt(12)
	v_pk_add_f32 v[50:51], v[50:51], v[170:171]
	v_pk_add_f32 v[48:49], v[48:49], v[168:169]
	s_waitcnt vmcnt(11)
	v_pk_add_f32 v[46:47], v[46:47], v[174:175]
	v_pk_add_f32 v[44:45], v[44:45], v[172:173]
	s_waitcnt vmcnt(10)
	v_pk_add_f32 v[42:43], v[42:43], v[178:179]
	v_pk_add_f32 v[40:41], v[40:41], v[176:177]
	s_waitcnt vmcnt(9)
	v_pk_add_f32 v[38:39], v[38:39], v[182:183]
	v_pk_add_f32 v[36:37], v[36:37], v[180:181]
	s_waitcnt vmcnt(8)
	v_pk_add_f32 v[34:35], v[34:35], v[186:187]
	v_pk_add_f32 v[32:33], v[32:33], v[184:185]
	s_waitcnt vmcnt(7)
	v_pk_add_f32 v[30:31], v[30:31], v[190:191]
	v_pk_add_f32 v[28:29], v[28:29], v[188:189]
	s_waitcnt vmcnt(6)
	v_pk_add_f32 v[26:27], v[26:27], v[194:195]
	v_pk_add_f32 v[24:25], v[24:25], v[192:193]
	s_waitcnt vmcnt(5)
	v_pk_add_f32 v[22:23], v[22:23], v[198:199]
	v_pk_add_f32 v[20:21], v[20:21], v[196:197]
	s_waitcnt vmcnt(4)
	v_pk_add_f32 v[18:19], v[18:19], v[202:203]
	v_pk_add_f32 v[16:17], v[16:17], v[200:201]
	s_waitcnt vmcnt(3)
	v_pk_add_f32 v[14:15], v[14:15], v[206:207]
	v_pk_add_f32 v[12:13], v[12:13], v[204:205]
	s_waitcnt vmcnt(2)
	v_pk_add_f32 v[10:11], v[10:11], v[222:223]
	v_pk_add_f32 v[8:9], v[8:9], v[220:221]
	s_waitcnt vmcnt(1)
	v_pk_add_f32 v[6:7], v[6:7], v[226:227]
	v_pk_add_f32 v[4:5], v[4:5], v[224:225]
	s_waitcnt vmcnt(0)
	v_pk_add_f32 v[2:3], v[2:3], v[230:231]
	v_pk_add_f32 v[0:1], v[0:1], v[228:229]
	global_store_dwordx4 v[140:141], v[126:129], off offset:0
	global_store_dwordx4 v[140:141], v[122:125], off offset:16
	global_store_dwordx4 v[140:141], v[118:121], off offset:512
	global_store_dwordx4 v[140:141], v[114:117], off offset:528
	global_store_dwordx4 v[236:237], v[110:113], off offset:0
	global_store_dwordx4 v[236:237], v[106:109], off offset:16
	global_store_dwordx4 v[236:237], v[102:105], off offset:512
	global_store_dwordx4 v[236:237], v[98:101], off offset:528
	global_store_dwordx4 v[238:239], v[94:97], off offset:0
	global_store_dwordx4 v[238:239], v[90:93], off offset:16
	global_store_dwordx4 v[238:239], v[86:89], off offset:512
	global_store_dwordx4 v[238:239], v[82:85], off offset:528
	global_store_dwordx4 v[240:241], v[78:81], off offset:0
	global_store_dwordx4 v[240:241], v[74:77], off offset:16
	global_store_dwordx4 v[240:241], v[70:73], off offset:512
	global_store_dwordx4 v[240:241], v[66:69], off offset:528
	global_store_dwordx4 v[242:243], v[60:63], off offset:0
	global_store_dwordx4 v[242:243], v[56:59], off offset:16
	global_store_dwordx4 v[242:243], v[52:55], off offset:512
	global_store_dwordx4 v[242:243], v[48:51], off offset:528
	global_store_dwordx4 v[244:245], v[44:47], off offset:0
	global_store_dwordx4 v[244:245], v[40:43], off offset:16
	global_store_dwordx4 v[244:245], v[36:39], off offset:512
	global_store_dwordx4 v[244:245], v[32:35], off offset:528
	global_store_dwordx4 v[246:247], v[28:31], off offset:0
	global_store_dwordx4 v[246:247], v[24:27], off offset:16
	global_store_dwordx4 v[246:247], v[20:23], off offset:512
	global_store_dwordx4 v[246:247], v[16:19], off offset:528
	global_store_dwordx4 v[248:249], v[12:15], off offset:0
	global_store_dwordx4 v[248:249], v[8:11], off offset:16
	global_store_dwordx4 v[248:249], v[4:7], off offset:512
	global_store_dwordx4 v[248:249], v[0:3], off offset:528
	s_mov_b64 s[0:1], -1
	s_and_b64 vcc, exec, s[8:9]
	s_cbranch_vccnz .LBB0_1000
	s_andn2_b64 vcc, exec, s[16:17]
	s_cbranch_vccnz .LBB0_999
	s_barrier
	s_branch .LBB0_999

.LBB0_1356:
	v_lshl_add_u32 v150, s24, 8, v143
	v_lshl_or_b32 v148, s50, 8, v153
	v_ashrrev_i32_e32 v151, 31, v150
	v_ashrrev_i32_e32 v149, 31, v148
	v_lshlrev_b64 v[140:141], 10, v[150:151]
	v_lshl_add_u64 v[140:141], v[140:141], 0, v[148:149]
	v_lshlrev_b64 v[140:141], 2, v[140:141]
	v_lshl_add_u64 v[160:161], s[12:13], 0, v[140:141]
	v_add_u32_e32 v236, 0x10000, v140
	v_add_u32_e32 v237, 0x20000, v140
	v_add_u32_e32 v238, 0x30000, v140
	v_add_u32_e32 v239, 0x80000, v140
	v_add_u32_e32 v240, 0x90000, v140
	v_add_u32_e32 v241, 0xa0000, v140
	v_add_u32_e32 v242, 0xb0000, v140
	global_load_dwordx4 v[156:159], v140, s[12:13] offset:0
	global_load_dwordx4 v[160:163], v140, s[12:13] offset:16
	global_load_dwordx4 v[164:167], v140, s[12:13] offset:512
	global_load_dwordx4 v[168:171], v140, s[12:13] offset:528
	global_load_dwordx4 v[172:175], v236, s[12:13] offset:0
	global_load_dwordx4 v[176:179], v236, s[12:13] offset:16
	global_load_dwordx4 v[180:183], v236, s[12:13] offset:512
	global_load_dwordx4 v[184:187], v236, s[12:13] offset:528
	global_load_dwordx4 v[188:191], v237, s[12:13] offset:0
	global_load_dwordx4 v[192:195], v237, s[12:13] offset:16
	global_load_dwordx4 v[196:199], v237, s[12:13] offset:512
	global_load_dwordx4 v[200:203], v237, s[12:13] offset:528
	global_load_dwordx4 v[204:207], v238, s[12:13] offset:0
	global_load_dwordx4 v[220:223], v238, s[12:13] offset:16
	global_load_dwordx4 v[224:227], v238, s[12:13] offset:512
	global_load_dwordx4 v[228:231], v238, s[12:13] offset:528
	s_waitcnt vmcnt(15)
	v_pk_add_f32 v[128:129], v[128:129], v[158:159]
	v_pk_add_f32 v[126:127], v[126:127], v[156:157]
	global_load_dwordx4 v[156:159], v239, s[12:13] offset:0
	s_waitcnt vmcnt(15)
	v_pk_add_f32 v[124:125], v[124:125], v[162:163]
	v_pk_add_f32 v[122:123], v[122:123], v[160:161]
	global_load_dwordx4 v[160:163], v239, s[12:13] offset:16
	s_waitcnt vmcnt(15)
	v_pk_add_f32 v[120:121], v[120:121], v[166:167]
	v_pk_add_f32 v[118:119], v[118:119], v[164:165]
	global_load_dwordx4 v[164:167], v239, s[12:13] offset:512
	s_waitcnt vmcnt(15)
	v_pk_add_f32 v[116:117], v[116:117], v[170:171]
	v_pk_add_f32 v[114:115], v[114:115], v[168:169]
	global_load_dwordx4 v[168:171], v239, s[12:13] offset:528
	s_waitcnt vmcnt(15)
	v_pk_add_f32 v[112:113], v[112:113], v[174:175]
	v_pk_add_f32 v[110:111], v[110:111], v[172:173]
	global_load_dwordx4 v[172:175], v240, s[12:13] offset:0
	s_waitcnt vmcnt(15)
	v_pk_add_f32 v[108:109], v[108:109], v[178:179]
	v_pk_add_f32 v[106:107], v[106:107], v[176:177]
	global_load_dwordx4 v[176:179], v240, s[12:13] offset:16
	s_waitcnt vmcnt(15)
	v_pk_add_f32 v[104:105], v[104:105], v[182:183]
	v_pk_add_f32 v[102:103], v[102:103], v[180:181]
	global_load_dwordx4 v[180:183], v240, s[12:13] offset:512
	s_waitcnt vmcnt(15)
	v_pk_add_f32 v[100:101], v[100:101], v[186:187]
	v_pk_add_f32 v[98:99], v[98:99], v[184:185]
	global_load_dwordx4 v[184:187], v240, s[12:13] offset:528
	s_waitcnt vmcnt(15)
	v_pk_add_f32 v[96:97], v[96:97], v[190:191]
	v_pk_add_f32 v[94:95], v[94:95], v[188:189]
	global_load_dwordx4 v[188:191], v241, s[12:13] offset:0
	s_waitcnt vmcnt(15)
	v_pk_add_f32 v[92:93], v[92:93], v[194:195]
	v_pk_add_f32 v[90:91], v[90:91], v[192:193]
	global_load_dwordx4 v[192:195], v241, s[12:13] offset:16
	s_waitcnt vmcnt(15)
	v_pk_add_f32 v[88:89], v[88:89], v[198:199]
	v_pk_add_f32 v[86:87], v[86:87], v[196:197]
	global_load_dwordx4 v[196:199], v241, s[12:13] offset:512
	s_waitcnt vmcnt(15)
	v_pk_add_f32 v[84:85], v[84:85], v[202:203]
	v_pk_add_f32 v[82:83], v[82:83], v[200:201]
	global_load_dwordx4 v[200:203], v241, s[12:13] offset:528
	s_waitcnt vmcnt(15)
	v_pk_add_f32 v[80:81], v[80:81], v[206:207]
	v_pk_add_f32 v[78:79], v[78:79], v[204:205]
	global_load_dwordx4 v[204:207], v242, s[12:13] offset:0
	s_waitcnt vmcnt(15)
	v_pk_add_f32 v[76:77], v[76:77], v[222:223]
	v_pk_add_f32 v[74:75], v[74:75], v[220:221]
	global_load_dwordx4 v[220:223], v242, s[12:13] offset:16
	s_waitcnt vmcnt(15)
	v_pk_add_f32 v[72:73], v[72:73], v[226:227]
	v_pk_add_f32 v[70:71], v[70:71], v[224:225]
	global_load_dwordx4 v[224:227], v242, s[12:13] offset:512
	s_waitcnt vmcnt(15)
	v_pk_add_f32 v[68:69], v[68:69], v[230:231]
	v_pk_add_f32 v[66:67], v[66:67], v[228:229]
	global_load_dwordx4 v[228:231], v242, s[12:13] offset:528
	s_waitcnt vmcnt(15)
	v_pk_add_f32 v[62:63], v[62:63], v[158:159]
	v_pk_add_f32 v[60:61], v[60:61], v[156:157]
	s_waitcnt vmcnt(14)
	v_pk_add_f32 v[58:59], v[58:59], v[162:163]
	v_pk_add_f32 v[56:57], v[56:57], v[160:161]
	s_waitcnt vmcnt(13)
	v_pk_add_f32 v[54:55], v[54:55], v[166:167]
	v_pk_add_f32 v[52:53], v[52:53], v[164:165]
	s_waitcnt vmcnt(12)
	v_pk_add_f32 v[50:51], v[50:51], v[170:171]
	v_pk_add_f32 v[48:49], v[48:49], v[168:169]
	s_waitcnt vmcnt(11)
	v_pk_add_f32 v[46:47], v[46:47], v[174:175]
	v_pk_add_f32 v[44:45], v[44:45], v[172:173]
	s_waitcnt vmcnt(10)
	v_pk_add_f32 v[42:43], v[42:43], v[178:179]
	v_pk_add_f32 v[40:41], v[40:41], v[176:177]
	s_waitcnt vmcnt(9)
	v_pk_add_f32 v[38:39], v[38:39], v[182:183]
	v_pk_add_f32 v[36:37], v[36:37], v[180:181]
	s_waitcnt vmcnt(8)
	v_pk_add_f32 v[34:35], v[34:35], v[186:187]
	v_pk_add_f32 v[32:33], v[32:33], v[184:185]
	s_waitcnt vmcnt(7)
	v_pk_add_f32 v[30:31], v[30:31], v[190:191]
	v_pk_add_f32 v[28:29], v[28:29], v[188:189]
	s_waitcnt vmcnt(6)
	v_pk_add_f32 v[26:27], v[26:27], v[194:195]
	v_pk_add_f32 v[24:25], v[24:25], v[192:193]
	s_waitcnt vmcnt(5)
	v_pk_add_f32 v[22:23], v[22:23], v[198:199]
	v_pk_add_f32 v[20:21], v[20:21], v[196:197]
	s_waitcnt vmcnt(4)
	v_pk_add_f32 v[18:19], v[18:19], v[202:203]
	v_pk_add_f32 v[16:17], v[16:17], v[200:201]
	s_waitcnt vmcnt(3)
	v_pk_add_f32 v[14:15], v[14:15], v[206:207]
	v_pk_add_f32 v[12:13], v[12:13], v[204:205]
	s_waitcnt vmcnt(2)
	v_pk_add_f32 v[10:11], v[10:11], v[222:223]
	v_pk_add_f32 v[8:9], v[8:9], v[220:221]
	s_waitcnt vmcnt(1)
	v_pk_add_f32 v[6:7], v[6:7], v[226:227]
	v_pk_add_f32 v[4:5], v[4:5], v[224:225]
	s_waitcnt vmcnt(0)
	v_pk_add_f32 v[2:3], v[2:3], v[230:231]
	v_pk_add_f32 v[0:1], v[0:1], v[228:229]
	global_store_dwordx4 v140, v[126:129], s[40:41] offset:0
	global_store_dwordx4 v140, v[122:125], s[40:41] offset:16
	global_store_dwordx4 v140, v[118:121], s[40:41] offset:512
	global_store_dwordx4 v140, v[114:117], s[40:41] offset:528
	global_store_dwordx4 v236, v[110:113], s[40:41] offset:0
	global_store_dwordx4 v236, v[106:109], s[40:41] offset:16
	global_store_dwordx4 v236, v[102:105], s[40:41] offset:512
	global_store_dwordx4 v236, v[98:101], s[40:41] offset:528
	global_store_dwordx4 v237, v[94:97], s[40:41] offset:0
	global_store_dwordx4 v237, v[90:93], s[40:41] offset:16
	global_store_dwordx4 v237, v[86:89], s[40:41] offset:512
	global_store_dwordx4 v237, v[82:85], s[40:41] offset:528
	global_store_dwordx4 v238, v[78:81], s[40:41] offset:0
	global_store_dwordx4 v238, v[74:77], s[40:41] offset:16
	global_store_dwordx4 v238, v[70:73], s[40:41] offset:512
	global_store_dwordx4 v238, v[66:69], s[40:41] offset:528
	global_store_dwordx4 v239, v[60:63], s[40:41] offset:0
	global_store_dwordx4 v239, v[56:59], s[40:41] offset:16
	global_store_dwordx4 v239, v[52:55], s[40:41] offset:512
	global_store_dwordx4 v239, v[48:51], s[40:41] offset:528
	global_store_dwordx4 v240, v[44:47], s[40:41] offset:0
	global_store_dwordx4 v240, v[40:43], s[40:41] offset:16
	global_store_dwordx4 v240, v[36:39], s[40:41] offset:512
	global_store_dwordx4 v240, v[32:35], s[40:41] offset:528
	global_store_dwordx4 v241, v[28:31], s[40:41] offset:0
	global_store_dwordx4 v241, v[24:27], s[40:41] offset:16
	global_store_dwordx4 v241, v[20:23], s[40:41] offset:512
	global_store_dwordx4 v241, v[16:19], s[40:41] offset:528
	global_store_dwordx4 v242, v[12:15], s[40:41] offset:0
	global_store_dwordx4 v242, v[8:11], s[40:41] offset:16
	global_store_dwordx4 v242, v[4:7], s[40:41] offset:512
	global_store_dwordx4 v242, v[0:3], s[40:41] offset:528
	s_mov_b64 s[0:1], -1
	s_andn2_b64 vcc, exec, s[8:9]
	s_cbranch_vccnz .LBB0_1345
	s_andn2_b64 vcc, exec, s[10:11]
	s_cbranch_vccnz .LBB0_1344
	s_barrier
	s_branch .LBB0_1344

.LBB0_1582:
	v_lshl_add_u32 v150, s37, 8, v143
	v_lshl_or_b32 v140, s38, 8, v153
	v_ashrrev_i32_e32 v151, 31, v150
	v_ashrrev_i32_e32 v141, 31, v140
	v_lshlrev_b64 v[144:145], 12, v[150:151]
	v_lshl_add_u64 v[144:145], s[40:41], 0, v[144:145]
	v_lshlrev_b64 v[148:149], 2, v[140:141]
	v_lshl_add_u64 v[140:141], v[144:145], 0, v[148:149]
	s_mov_b64 s[0:1], 0x10000
	v_lshl_add_u64 v[236:237], v[140:141], 0, s[0:1]
	s_mov_b64 s[0:1], 0x20000
	v_lshl_add_u64 v[238:239], v[140:141], 0, s[0:1]
	s_mov_b64 s[0:1], 0x30000
	v_lshl_add_u64 v[240:241], v[140:141], 0, s[0:1]
	s_mov_b64 s[0:1], 0x80000
	v_lshl_add_u64 v[242:243], v[140:141], 0, s[0:1]
	s_mov_b64 s[0:1], 0x90000
	v_lshl_add_u64 v[244:245], v[140:141], 0, s[0:1]
	s_mov_b64 s[0:1], 0xa0000
	v_lshl_add_u64 v[246:247], v[140:141], 0, s[0:1]
	s_mov_b64 s[0:1], 0xb0000
	v_lshl_add_u64 v[248:249], v[140:141], 0, s[0:1]
	global_load_dwordx4 v[156:159], v[140:141], off offset:0
	global_load_dwordx4 v[160:163], v[140:141], off offset:16
	global_load_dwordx4 v[164:167], v[140:141], off offset:512
	global_load_dwordx4 v[168:171], v[140:141], off offset:528
	global_load_dwordx4 v[172:175], v[236:237], off offset:0
	global_load_dwordx4 v[176:179], v[236:237], off offset:16
	global_load_dwordx4 v[180:183], v[236:237], off offset:512
	global_load_dwordx4 v[184:187], v[236:237], off offset:528
	global_load_dwordx4 v[188:191], v[238:239], off offset:0
	global_load_dwordx4 v[192:195], v[238:239], off offset:16
	global_load_dwordx4 v[196:199], v[238:239], off offset:512
	global_load_dwordx4 v[200:203], v[238:239], off offset:528
	global_load_dwordx4 v[204:207], v[240:241], off offset:0
	global_load_dwordx4 v[220:223], v[240:241], off offset:16
	global_load_dwordx4 v[224:227], v[240:241], off offset:512
	global_load_dwordx4 v[228:231], v[240:241], off offset:528
	s_waitcnt vmcnt(15)
	v_pk_add_f32 v[128:129], v[128:129], v[158:159]
	v_pk_add_f32 v[126:127], v[126:127], v[156:157]
	global_load_dwordx4 v[156:159], v[242:243], off offset:0
	s_waitcnt vmcnt(15)
	v_pk_add_f32 v[124:125], v[124:125], v[162:163]
	v_pk_add_f32 v[122:123], v[122:123], v[160:161]
	global_load_dwordx4 v[160:163], v[242:243], off offset:16
	s_waitcnt vmcnt(15)
	v_pk_add_f32 v[120:121], v[120:121], v[166:167]
	v_pk_add_f32 v[118:119], v[118:119], v[164:165]
	global_load_dwordx4 v[164:167], v[242:243], off offset:512
	s_waitcnt vmcnt(15)
	v_pk_add_f32 v[116:117], v[116:117], v[170:171]
	v_pk_add_f32 v[114:115], v[114:115], v[168:169]
	global_load_dwordx4 v[168:171], v[242:243], off offset:528
	s_waitcnt vmcnt(15)
	v_pk_add_f32 v[112:113], v[112:113], v[174:175]
	v_pk_add_f32 v[110:111], v[110:111], v[172:173]
	global_load_dwordx4 v[172:175], v[244:245], off offset:0
	s_waitcnt vmcnt(15)
	v_pk_add_f32 v[108:109], v[108:109], v[178:179]
	v_pk_add_f32 v[106:107], v[106:107], v[176:177]
	global_load_dwordx4 v[176:179], v[244:245], off offset:16
	s_waitcnt vmcnt(15)
	v_pk_add_f32 v[104:105], v[104:105], v[182:183]
	v_pk_add_f32 v[102:103], v[102:103], v[180:181]
	global_load_dwordx4 v[180:183], v[244:245], off offset:512
	s_waitcnt vmcnt(15)
	v_pk_add_f32 v[100:101], v[100:101], v[186:187]
	v_pk_add_f32 v[98:99], v[98:99], v[184:185]
	global_load_dwordx4 v[184:187], v[244:245], off offset:528
	s_waitcnt vmcnt(15)
	v_pk_add_f32 v[96:97], v[96:97], v[190:191]
	v_pk_add_f32 v[94:95], v[94:95], v[188:189]
	global_load_dwordx4 v[188:191], v[246:247], off offset:0
	s_waitcnt vmcnt(15)
	v_pk_add_f32 v[92:93], v[92:93], v[194:195]
	v_pk_add_f32 v[90:91], v[90:91], v[192:193]
	global_load_dwordx4 v[192:195], v[246:247], off offset:16
	s_waitcnt vmcnt(15)
	v_pk_add_f32 v[88:89], v[88:89], v[198:199]
	v_pk_add_f32 v[86:87], v[86:87], v[196:197]
	global_load_dwordx4 v[196:199], v[246:247], off offset:512
	s_waitcnt vmcnt(15)
	v_pk_add_f32 v[84:85], v[84:85], v[202:203]
	v_pk_add_f32 v[82:83], v[82:83], v[200:201]
	global_load_dwordx4 v[200:203], v[246:247], off offset:528
	s_waitcnt vmcnt(15)
	v_pk_add_f32 v[80:81], v[80:81], v[206:207]
	v_pk_add_f32 v[78:79], v[78:79], v[204:205]
	global_load_dwordx4 v[204:207], v[248:249], off offset:0
	s_waitcnt vmcnt(15)
	v_pk_add_f32 v[76:77], v[76:77], v[222:223]
	v_pk_add_f32 v[74:75], v[74:75], v[220:221]
	global_load_dwordx4 v[220:223], v[248:249], off offset:16
	s_waitcnt vmcnt(15)
	v_pk_add_f32 v[72:73], v[72:73], v[226:227]
	v_pk_add_f32 v[70:71], v[70:71], v[224:225]
	global_load_dwordx4 v[224:227], v[248:249], off offset:512
	s_waitcnt vmcnt(15)
	v_pk_add_f32 v[68:69], v[68:69], v[230:231]
	v_pk_add_f32 v[66:67], v[66:67], v[228:229]
	global_load_dwordx4 v[228:231], v[248:249], off offset:528
	s_waitcnt vmcnt(15)
	v_pk_add_f32 v[62:63], v[62:63], v[158:159]
	v_pk_add_f32 v[60:61], v[60:61], v[156:157]
	s_waitcnt vmcnt(14)
	v_pk_add_f32 v[58:59], v[58:59], v[162:163]
	v_pk_add_f32 v[56:57], v[56:57], v[160:161]
	s_waitcnt vmcnt(13)
	v_pk_add_f32 v[54:55], v[54:55], v[166:167]
	v_pk_add_f32 v[52:53], v[52:53], v[164:165]
	s_waitcnt vmcnt(12)
	v_pk_add_f32 v[50:51], v[50:51], v[170:171]
	v_pk_add_f32 v[48:49], v[48:49], v[168:169]
	s_waitcnt vmcnt(11)
	v_pk_add_f32 v[46:47], v[46:47], v[174:175]
	v_pk_add_f32 v[44:45], v[44:45], v[172:173]
	s_waitcnt vmcnt(10)
	v_pk_add_f32 v[42:43], v[42:43], v[178:179]
	v_pk_add_f32 v[40:41], v[40:41], v[176:177]
	s_waitcnt vmcnt(9)
	v_pk_add_f32 v[38:39], v[38:39], v[182:183]
	v_pk_add_f32 v[36:37], v[36:37], v[180:181]
	s_waitcnt vmcnt(8)
	v_pk_add_f32 v[34:35], v[34:35], v[186:187]
	v_pk_add_f32 v[32:33], v[32:33], v[184:185]
	s_waitcnt vmcnt(7)
	v_pk_add_f32 v[30:31], v[30:31], v[190:191]
	v_pk_add_f32 v[28:29], v[28:29], v[188:189]
	s_waitcnt vmcnt(6)
	v_pk_add_f32 v[26:27], v[26:27], v[194:195]
	v_pk_add_f32 v[24:25], v[24:25], v[192:193]
	s_waitcnt vmcnt(5)
	v_pk_add_f32 v[22:23], v[22:23], v[198:199]
	v_pk_add_f32 v[20:21], v[20:21], v[196:197]
	s_waitcnt vmcnt(4)
	v_pk_add_f32 v[18:19], v[18:19], v[202:203]
	v_pk_add_f32 v[16:17], v[16:17], v[200:201]
	s_waitcnt vmcnt(3)
	v_pk_add_f32 v[14:15], v[14:15], v[206:207]
	v_pk_add_f32 v[12:13], v[12:13], v[204:205]
	s_waitcnt vmcnt(2)
	v_pk_add_f32 v[10:11], v[10:11], v[222:223]
	v_pk_add_f32 v[8:9], v[8:9], v[220:221]
	s_waitcnt vmcnt(1)
	v_pk_add_f32 v[6:7], v[6:7], v[226:227]
	v_pk_add_f32 v[4:5], v[4:5], v[224:225]
	s_waitcnt vmcnt(0)
	v_pk_add_f32 v[2:3], v[2:3], v[230:231]
	v_pk_add_f32 v[0:1], v[0:1], v[228:229]
	global_store_dwordx4 v[140:141], v[126:129], off offset:0
	global_store_dwordx4 v[140:141], v[122:125], off offset:16
	global_store_dwordx4 v[140:141], v[118:121], off offset:512
	global_store_dwordx4 v[140:141], v[114:117], off offset:528
	global_store_dwordx4 v[236:237], v[110:113], off offset:0
	global_store_dwordx4 v[236:237], v[106:109], off offset:16
	global_store_dwordx4 v[236:237], v[102:105], off offset:512
	global_store_dwordx4 v[236:237], v[98:101], off offset:528
	global_store_dwordx4 v[238:239], v[94:97], off offset:0
	global_store_dwordx4 v[238:239], v[90:93], off offset:16
	global_store_dwordx4 v[238:239], v[86:89], off offset:512
	global_store_dwordx4 v[238:239], v[82:85], off offset:528
	global_store_dwordx4 v[240:241], v[78:81], off offset:0
	global_store_dwordx4 v[240:241], v[74:77], off offset:16
	global_store_dwordx4 v[240:241], v[70:73], off offset:512
	global_store_dwordx4 v[240:241], v[66:69], off offset:528
	global_store_dwordx4 v[242:243], v[60:63], off offset:0
	global_store_dwordx4 v[242:243], v[56:59], off offset:16
	global_store_dwordx4 v[242:243], v[52:55], off offset:512
	global_store_dwordx4 v[242:243], v[48:51], off offset:528
	global_store_dwordx4 v[244:245], v[44:47], off offset:0
	global_store_dwordx4 v[244:245], v[40:43], off offset:16
	global_store_dwordx4 v[244:245], v[36:39], off offset:512
	global_store_dwordx4 v[244:245], v[32:35], off offset:528
	global_store_dwordx4 v[246:247], v[28:31], off offset:0
	global_store_dwordx4 v[246:247], v[24:27], off offset:16
	global_store_dwordx4 v[246:247], v[20:23], off offset:512
	global_store_dwordx4 v[246:247], v[16:19], off offset:528
	global_store_dwordx4 v[248:249], v[12:15], off offset:0
	global_store_dwordx4 v[248:249], v[8:11], off offset:16
	global_store_dwordx4 v[248:249], v[4:7], off offset:512
	global_store_dwordx4 v[248:249], v[0:3], off offset:528
	s_mov_b64 s[0:1], -1
	s_and_b64 vcc, exec, s[8:9]
	s_cbranch_vccnz .LBB0_1567
	s_andn2_b64 vcc, exec, s[12:13]
	s_cbranch_vccnz .LBB0_1566
	s_barrier
	s_branch .LBB0_1566
